# GEMM K loops: all setprio toggles removed, no static raise (both half-workgroups at equal priority)
# speedup vs baseline: 1.0056x; 1.0056x over previous
.LBB0_163:
	ds_read_b128 v[152:155], v149
	ds_read_b128 v[156:159], v149 offset:1024
	ds_read_b128 v[160:163], v149 offset:2048
	ds_read_b128 v[164:167], v149 offset:3072
	ds_read_b128 v[168:171], v150
	ds_read_b128 v[172:175], v150 offset:1024
	ds_read_b128 v[176:179], v150 offset:2048
	ds_read_b128 v[180:183], v150 offset:3072
	s_add_u32 s24, s22, 0xfff80080
	s_addc_u32 s25, s23, -1
	s_cmp_eq_u32 s58, 28
	s_cselect_b32 s27, s15, s25
	s_cselect_b32 s26, s54, s24
	s_cselect_b32 s25, s13, s57
	s_cselect_b32 s24, s55, s56
	s_add_u32 s98, s24, s6
	s_addc_u32 s99, s25, s7
	s_add_u32 s100, s26, s6
	s_addc_u32 s101, s27, s7
	s_add_i32 m0, s21, 0xc000
	ds_read_b128 v[184:187], v151
	ds_read_b128 v[188:191], v151 offset:1024
	ds_read_b128 v[192:195], v151 offset:2048
	ds_read_b128 v[196:199], v151 offset:3072
	ds_read_b128 v[200:203], v151 offset:4096
	ds_read_b128 v[204:207], v151 offset:5120
	ds_read_b128 v[208:211], v151 offset:6144
	ds_read_b128 v[212:215], v151 offset:7168
	global_load_lds_dwordx4 v136, s[22:23]
	s_add_i32 m0, s21, 0xe000
	s_nop 0
	global_load_lds_dwordx4 v138, s[22:23]
	s_waitcnt vmcnt(8)
	s_waitcnt lgkmcnt(0)
	s_barrier
	s_waitcnt lgkmcnt(0)
	v_mfma_f32_16x16x32_bf16 v[124:127], v[152:155], v[184:187], v[124:127]
	v_mfma_f32_16x16x32_bf16 v[120:123], v[160:163], v[184:187], v[120:123]
	v_mfma_f32_16x16x32_bf16 v[116:119], v[152:155], v[192:195], v[116:119]
	v_mfma_f32_16x16x32_bf16 v[108:111], v[160:163], v[192:195], v[108:111]
	v_mfma_f32_16x16x32_bf16 v[100:103], v[152:155], v[200:203], v[100:103]
	v_mfma_f32_16x16x32_bf16 v[92:95], v[160:163], v[200:203], v[92:95]
	v_mfma_f32_16x16x32_bf16 v[84:87], v[152:155], v[208:211], v[84:87]
	v_mfma_f32_16x16x32_bf16 v[76:79], v[160:163], v[208:211], v[76:79]
	v_mfma_f32_16x16x32_bf16 v[124:127], v[156:159], v[188:191], v[124:127]
	v_mfma_f32_16x16x32_bf16 v[120:123], v[164:167], v[188:191], v[120:123]
	v_mfma_f32_16x16x32_bf16 v[116:119], v[156:159], v[196:199], v[116:119]
	v_mfma_f32_16x16x32_bf16 v[108:111], v[164:167], v[196:199], v[108:111]
	v_mfma_f32_16x16x32_bf16 v[100:103], v[156:159], v[204:207], v[100:103]
	v_mfma_f32_16x16x32_bf16 v[92:95], v[164:167], v[204:207], v[92:95]
	v_mfma_f32_16x16x32_bf16 v[84:87], v[156:159], v[212:215], v[84:87]
	v_mfma_f32_16x16x32_bf16 v[76:79], v[164:167], v[212:215], v[76:79]
	v_mfma_f32_16x16x32_bf16 v[112:115], v[168:171], v[184:187], v[112:115]
	v_mfma_f32_16x16x32_bf16 v[104:107], v[176:179], v[184:187], v[104:107]
	v_mfma_f32_16x16x32_bf16 v[96:99], v[168:171], v[192:195], v[96:99]
	v_mfma_f32_16x16x32_bf16 v[88:91], v[176:179], v[192:195], v[88:91]
	v_mfma_f32_16x16x32_bf16 v[80:83], v[168:171], v[200:203], v[80:83]
	v_mfma_f32_16x16x32_bf16 v[72:75], v[176:179], v[200:203], v[72:75]
	v_mfma_f32_16x16x32_bf16 v[68:71], v[168:171], v[208:211], v[68:71]
	v_mfma_f32_16x16x32_bf16 v[64:67], v[176:179], v[208:211], v[64:67]
	v_mfma_f32_16x16x32_bf16 v[112:115], v[172:175], v[188:191], v[112:115]
	v_mfma_f32_16x16x32_bf16 v[104:107], v[180:183], v[188:191], v[104:107]
	v_mfma_f32_16x16x32_bf16 v[96:99], v[172:175], v[196:199], v[96:99]
	v_mfma_f32_16x16x32_bf16 v[88:91], v[180:183], v[196:199], v[88:91]
	v_mfma_f32_16x16x32_bf16 v[80:83], v[172:175], v[204:207], v[80:83]
	v_mfma_f32_16x16x32_bf16 v[72:75], v[180:183], v[204:207], v[72:75]
	v_mfma_f32_16x16x32_bf16 v[68:71], v[172:175], v[212:215], v[68:71]
	v_mfma_f32_16x16x32_bf16 v[64:67], v[180:183], v[212:215], v[64:67]
	s_barrier
	s_add_i32 s59, s43, s28
	s_mov_b32 m0, s59
	ds_read_b128 v[184:187], v151 offset:16384
	ds_read_b128 v[188:191], v151 offset:17408
	ds_read_b128 v[192:195], v151 offset:18432
	ds_read_b128 v[196:199], v151 offset:19456
	ds_read_b128 v[200:203], v151 offset:20480
	ds_read_b128 v[204:207], v151 offset:21504
	ds_read_b128 v[208:211], v151 offset:22528
	ds_read_b128 v[212:215], v151 offset:23552
	global_load_lds_dwordx4 v130, s[24:25]
	s_add_i32 m0, s59, 0x2000
	s_add_u32 s62, s24, 0x200000
	s_addc_u32 s63, s25, 0
	s_add_i32 s59, s48, s28
	global_load_lds_dwordx4 v134, s[24:25]
	s_mov_b32 m0, s59
	s_nop 0
	global_load_lds_dwordx4 v130, s[62:63]
	s_add_i32 m0, s59, 0x2000
	s_nop 0
	global_load_lds_dwordx4 v134, s[62:63]
	s_mov_b32 m0, s21
	s_nop 0
	global_load_lds_dwordx4 v128, s[26:27]
	s_mov_b32 m0, s31
	s_nop 0
	global_load_lds_dwordx4 v132, s[26:27]
	s_waitcnt vmcnt(8)
	s_waitcnt lgkmcnt(0)
	s_barrier
	s_waitcnt lgkmcnt(0)
	v_mfma_f32_16x16x32_bf16 v[60:63], v[152:155], v[184:187], v[60:63]
	v_mfma_f32_16x16x32_bf16 v[56:59], v[160:163], v[184:187], v[56:59]
	v_mfma_f32_16x16x32_bf16 v[52:55], v[152:155], v[192:195], v[52:55]
	v_mfma_f32_16x16x32_bf16 v[44:47], v[160:163], v[192:195], v[44:47]
	v_mfma_f32_16x16x32_bf16 v[36:39], v[152:155], v[200:203], v[36:39]
	v_mfma_f32_16x16x32_bf16 v[28:31], v[160:163], v[200:203], v[28:31]
	v_mfma_f32_16x16x32_bf16 v[20:23], v[152:155], v[208:211], v[20:23]
	v_mfma_f32_16x16x32_bf16 v[12:15], v[160:163], v[208:211], v[12:15]
	v_mfma_f32_16x16x32_bf16 v[60:63], v[156:159], v[188:191], v[60:63]
	v_mfma_f32_16x16x32_bf16 v[56:59], v[164:167], v[188:191], v[56:59]
	v_mfma_f32_16x16x32_bf16 v[52:55], v[156:159], v[196:199], v[52:55]
	v_mfma_f32_16x16x32_bf16 v[44:47], v[164:167], v[196:199], v[44:47]
	v_mfma_f32_16x16x32_bf16 v[36:39], v[156:159], v[204:207], v[36:39]
	v_mfma_f32_16x16x32_bf16 v[28:31], v[164:167], v[204:207], v[28:31]
	v_mfma_f32_16x16x32_bf16 v[20:23], v[156:159], v[212:215], v[20:23]
	v_mfma_f32_16x16x32_bf16 v[12:15], v[164:167], v[212:215], v[12:15]
	v_mfma_f32_16x16x32_bf16 v[48:51], v[168:171], v[184:187], v[48:51]
	v_mfma_f32_16x16x32_bf16 v[40:43], v[176:179], v[184:187], v[40:43]
	v_mfma_f32_16x16x32_bf16 v[32:35], v[168:171], v[192:195], v[32:35]
	v_mfma_f32_16x16x32_bf16 v[24:27], v[176:179], v[192:195], v[24:27]
	v_mfma_f32_16x16x32_bf16 v[16:19], v[168:171], v[200:203], v[16:19]
	v_mfma_f32_16x16x32_bf16 v[8:11], v[176:179], v[200:203], v[8:11]
	v_mfma_f32_16x16x32_bf16 v[4:7], v[168:171], v[208:211], v[4:7]
	v_mfma_f32_16x16x32_bf16 v[0:3], v[176:179], v[208:211], v[0:3]
	v_mfma_f32_16x16x32_bf16 v[48:51], v[172:175], v[188:191], v[48:51]
	v_mfma_f32_16x16x32_bf16 v[40:43], v[180:183], v[188:191], v[40:43]
	v_mfma_f32_16x16x32_bf16 v[32:35], v[172:175], v[196:199], v[32:35]
	v_mfma_f32_16x16x32_bf16 v[24:27], v[180:183], v[196:199], v[24:27]
	v_mfma_f32_16x16x32_bf16 v[16:19], v[172:175], v[204:207], v[16:19]
	v_mfma_f32_16x16x32_bf16 v[8:11], v[180:183], v[204:207], v[8:11]
	v_mfma_f32_16x16x32_bf16 v[4:7], v[172:175], v[212:215], v[4:7]
	v_mfma_f32_16x16x32_bf16 v[0:3], v[180:183], v[212:215], v[0:3]
	s_barrier
	s_add_i32 s59, 0, 0x18000
	s_add_i32 s62, 0, 0x1c000
	v_add_u32_e32 v164, s59, v146
	v_add_u32_e32 v180, s62, v146
	ds_read_b128 v[152:155], v164
	ds_read_b128 v[156:159], v164 offset:1024
	ds_read_b128 v[160:163], v164 offset:2048
	ds_read_b128 v[164:167], v164 offset:3072
	ds_read_b128 v[168:171], v180
	ds_read_b128 v[172:175], v180 offset:1024
	ds_read_b128 v[176:179], v180 offset:2048
	ds_read_b128 v[180:183], v180 offset:3072
	s_add_u32 s26, s26, 0x80000
	s_addc_u32 s27, s27, 0
	s_mov_b32 m0, s34
	ds_read_b128 v[184:187], v151 offset:32768
	ds_read_b128 v[188:191], v151 offset:33792
	ds_read_b128 v[192:195], v151 offset:34816
	ds_read_b128 v[196:199], v151 offset:35840
	ds_read_b128 v[200:203], v151 offset:36864
	ds_read_b128 v[204:207], v151 offset:37888
	ds_read_b128 v[208:211], v151 offset:38912
	ds_read_b128 v[212:215], v151 offset:39936
	global_load_lds_dwordx4 v128, s[26:27]
	s_mov_b32 m0, s35
	s_nop 0
	global_load_lds_dwordx4 v132, s[26:27]
	s_waitcnt vmcnt(8)
	s_waitcnt lgkmcnt(0)
	s_barrier
	s_waitcnt lgkmcnt(0)
	v_mfma_f32_16x16x32_bf16 v[124:127], v[152:155], v[184:187], v[124:127]
	v_mfma_f32_16x16x32_bf16 v[120:123], v[160:163], v[184:187], v[120:123]
	v_mfma_f32_16x16x32_bf16 v[116:119], v[152:155], v[192:195], v[116:119]
	v_mfma_f32_16x16x32_bf16 v[108:111], v[160:163], v[192:195], v[108:111]
	v_mfma_f32_16x16x32_bf16 v[100:103], v[152:155], v[200:203], v[100:103]
	v_mfma_f32_16x16x32_bf16 v[92:95], v[160:163], v[200:203], v[92:95]
	v_mfma_f32_16x16x32_bf16 v[84:87], v[152:155], v[208:211], v[84:87]
	v_mfma_f32_16x16x32_bf16 v[76:79], v[160:163], v[208:211], v[76:79]
	v_mfma_f32_16x16x32_bf16 v[124:127], v[156:159], v[188:191], v[124:127]
	v_mfma_f32_16x16x32_bf16 v[120:123], v[164:167], v[188:191], v[120:123]
	v_mfma_f32_16x16x32_bf16 v[116:119], v[156:159], v[196:199], v[116:119]
	v_mfma_f32_16x16x32_bf16 v[108:111], v[164:167], v[196:199], v[108:111]
	v_mfma_f32_16x16x32_bf16 v[100:103], v[156:159], v[204:207], v[100:103]
	v_mfma_f32_16x16x32_bf16 v[92:95], v[164:167], v[204:207], v[92:95]
	v_mfma_f32_16x16x32_bf16 v[84:87], v[156:159], v[212:215], v[84:87]
	v_mfma_f32_16x16x32_bf16 v[76:79], v[164:167], v[212:215], v[76:79]
	v_mfma_f32_16x16x32_bf16 v[112:115], v[168:171], v[184:187], v[112:115]
	v_mfma_f32_16x16x32_bf16 v[104:107], v[176:179], v[184:187], v[104:107]
	v_mfma_f32_16x16x32_bf16 v[96:99], v[168:171], v[192:195], v[96:99]
	v_mfma_f32_16x16x32_bf16 v[88:91], v[176:179], v[192:195], v[88:91]
	v_mfma_f32_16x16x32_bf16 v[80:83], v[168:171], v[200:203], v[80:83]
	v_mfma_f32_16x16x32_bf16 v[72:75], v[176:179], v[200:203], v[72:75]
	v_mfma_f32_16x16x32_bf16 v[68:71], v[168:171], v[208:211], v[68:71]
	v_mfma_f32_16x16x32_bf16 v[64:67], v[176:179], v[208:211], v[64:67]
	v_mfma_f32_16x16x32_bf16 v[112:115], v[172:175], v[188:191], v[112:115]
	v_mfma_f32_16x16x32_bf16 v[104:107], v[180:183], v[188:191], v[104:107]
	v_mfma_f32_16x16x32_bf16 v[96:99], v[172:175], v[196:199], v[96:99]
	v_mfma_f32_16x16x32_bf16 v[88:91], v[180:183], v[196:199], v[88:91]
	v_mfma_f32_16x16x32_bf16 v[80:83], v[172:175], v[204:207], v[80:83]
	v_mfma_f32_16x16x32_bf16 v[72:75], v[180:183], v[204:207], v[72:75]
	v_mfma_f32_16x16x32_bf16 v[68:71], v[172:175], v[212:215], v[68:71]
	v_mfma_f32_16x16x32_bf16 v[64:67], v[180:183], v[212:215], v[64:67]
	s_barrier
	s_add_i32 s26, s59, s28
	s_mov_b32 m0, s26
	ds_read_b128 v[184:187], v151 offset:49152
	ds_read_b128 v[188:191], v151 offset:50176
	ds_read_b128 v[192:195], v151 offset:51200
	ds_read_b128 v[196:199], v151 offset:52224
	ds_read_b128 v[200:203], v151 offset:53248
	ds_read_b128 v[204:207], v151 offset:54272
	ds_read_b128 v[208:211], v151 offset:55296
	ds_read_b128 v[212:215], v151 offset:56320
	global_load_lds_dwordx4 v130, s[98:99]
	s_add_i32 m0, s26, 0x2000
	s_add_u32 s24, s24, 0x200080
	s_addc_u32 s25, s25, 0
	s_add_i32 s26, s62, s28
	global_load_lds_dwordx4 v134, s[98:99]
	s_mov_b32 m0, s26
	s_nop 0
	global_load_lds_dwordx4 v130, s[24:25]
	s_add_i32 m0, s26, 0x2000
	s_nop 0
	global_load_lds_dwordx4 v134, s[24:25]
	s_mov_b32 m0, s37
	s_nop 0
	global_load_lds_dwordx4 v128, s[100:101]
	s_mov_b32 m0, s38
	s_nop 0
	global_load_lds_dwordx4 v132, s[100:101]
	s_waitcnt vmcnt(8)
	s_waitcnt lgkmcnt(0)
	s_barrier
	s_waitcnt lgkmcnt(0)
	v_mfma_f32_16x16x32_bf16 v[60:63], v[152:155], v[184:187], v[60:63]
	v_mfma_f32_16x16x32_bf16 v[56:59], v[160:163], v[184:187], v[56:59]
	v_mfma_f32_16x16x32_bf16 v[52:55], v[152:155], v[192:195], v[52:55]
	v_mfma_f32_16x16x32_bf16 v[44:47], v[160:163], v[192:195], v[44:47]
	v_mfma_f32_16x16x32_bf16 v[36:39], v[152:155], v[200:203], v[36:39]
	v_mfma_f32_16x16x32_bf16 v[28:31], v[160:163], v[200:203], v[28:31]
	v_mfma_f32_16x16x32_bf16 v[20:23], v[152:155], v[208:211], v[20:23]
	v_mfma_f32_16x16x32_bf16 v[12:15], v[160:163], v[208:211], v[12:15]
	v_mfma_f32_16x16x32_bf16 v[60:63], v[156:159], v[188:191], v[60:63]
	v_mfma_f32_16x16x32_bf16 v[56:59], v[164:167], v[188:191], v[56:59]
	v_mfma_f32_16x16x32_bf16 v[52:55], v[156:159], v[196:199], v[52:55]
	v_mfma_f32_16x16x32_bf16 v[44:47], v[164:167], v[196:199], v[44:47]
	v_mfma_f32_16x16x32_bf16 v[36:39], v[156:159], v[204:207], v[36:39]
	v_mfma_f32_16x16x32_bf16 v[28:31], v[164:167], v[204:207], v[28:31]
	v_mfma_f32_16x16x32_bf16 v[20:23], v[156:159], v[212:215], v[20:23]
	v_mfma_f32_16x16x32_bf16 v[12:15], v[164:167], v[212:215], v[12:15]
	v_mfma_f32_16x16x32_bf16 v[48:51], v[168:171], v[184:187], v[48:51]
	v_mfma_f32_16x16x32_bf16 v[40:43], v[176:179], v[184:187], v[40:43]
	v_mfma_f32_16x16x32_bf16 v[32:35], v[168:171], v[192:195], v[32:35]
	v_mfma_f32_16x16x32_bf16 v[24:27], v[176:179], v[192:195], v[24:27]
	v_mfma_f32_16x16x32_bf16 v[16:19], v[168:171], v[200:203], v[16:19]
	v_mfma_f32_16x16x32_bf16 v[8:11], v[176:179], v[200:203], v[8:11]
	v_mfma_f32_16x16x32_bf16 v[4:7], v[168:171], v[208:211], v[4:7]
	v_mfma_f32_16x16x32_bf16 v[0:3], v[176:179], v[208:211], v[0:3]
	v_mfma_f32_16x16x32_bf16 v[48:51], v[172:175], v[188:191], v[48:51]
	v_mfma_f32_16x16x32_bf16 v[40:43], v[180:183], v[188:191], v[40:43]
	v_mfma_f32_16x16x32_bf16 v[32:35], v[172:175], v[196:199], v[32:35]
	v_mfma_f32_16x16x32_bf16 v[24:27], v[180:183], v[196:199], v[24:27]
	v_mfma_f32_16x16x32_bf16 v[16:19], v[172:175], v[204:207], v[16:19]
	v_mfma_f32_16x16x32_bf16 v[8:11], v[180:183], v[204:207], v[8:11]
	v_mfma_f32_16x16x32_bf16 v[4:7], v[172:175], v[212:215], v[4:7]
	v_mfma_f32_16x16x32_bf16 v[0:3], v[180:183], v[212:215], v[0:3]
	s_barrier
	s_add_i32 s58, s58, 2
	s_add_u32 s22, s22, 0x100
	s_addc_u32 s23, s23, 0
	s_add_u32 s56, s56, 0x100
	s_addc_u32 s57, s57, 0
	s_cmp_gt_u32 s58, 29
	s_cbranch_scc0 .LBB0_163
	s_and_b64 vcc, exec, s[10:11]
	s_cbranch_vccz .LBB0_166
	s_barrier

.LBB0_188:
	ds_read_b128 v[154:157], v149
	ds_read_b128 v[158:161], v149 offset:1024
	ds_read_b128 v[162:165], v149 offset:2048
	ds_read_b128 v[166:169], v149 offset:3072
	ds_read_b128 v[170:173], v150
	ds_read_b128 v[174:177], v150 offset:1024
	ds_read_b128 v[178:181], v150 offset:2048
	ds_read_b128 v[182:185], v150 offset:3072
	s_add_u32 s34, s30, 0xfff00080
	s_addc_u32 s35, s31, -1
	s_cmp_eq_u32 s79, 60
	s_cselect_b32 s37, s23, s35
	s_cselect_b32 s36, s73, s34
	s_cselect_b32 s35, s21, s78
	s_cselect_b32 s34, s74, s75
	s_add_u32 s98, s34, s10
	s_addc_u32 s99, s35, s11
	s_add_u32 s100, s36, s10
	s_addc_u32 s101, s37, s11
	s_add_i32 m0, s49, 0xc000
	ds_read_b128 v[186:189], v151
	ds_read_b128 v[190:193], v151 offset:1024
	ds_read_b128 v[194:197], v151 offset:2048
	ds_read_b128 v[198:201], v151 offset:3072
	ds_read_b128 v[202:205], v151 offset:4096
	ds_read_b128 v[206:209], v151 offset:5120
	ds_read_b128 v[210:213], v151 offset:6144
	ds_read_b128 v[214:217], v151 offset:7168
	global_load_lds_dwordx4 v136, s[30:31]
	s_add_i32 m0, s49, 0xe000
	s_nop 0
	global_load_lds_dwordx4 v138, s[30:31]
	s_waitcnt vmcnt(8)
	s_waitcnt lgkmcnt(0)
	s_barrier
	s_waitcnt lgkmcnt(0)
	v_mfma_f32_16x16x32_bf16 v[124:127], v[154:157], v[186:189], v[124:127]
	v_mfma_f32_16x16x32_bf16 v[120:123], v[162:165], v[186:189], v[120:123]
	v_mfma_f32_16x16x32_bf16 v[116:119], v[154:157], v[194:197], v[116:119]
	v_mfma_f32_16x16x32_bf16 v[112:115], v[162:165], v[194:197], v[112:115]
	v_mfma_f32_16x16x32_bf16 v[104:107], v[154:157], v[202:205], v[104:107]
	v_mfma_f32_16x16x32_bf16 v[96:99], v[162:165], v[202:205], v[96:99]
	v_mfma_f32_16x16x32_bf16 v[76:79], v[154:157], v[210:213], v[76:79]
	v_mfma_f32_16x16x32_bf16 v[72:75], v[162:165], v[210:213], v[72:75]
	v_mfma_f32_16x16x32_bf16 v[124:127], v[158:161], v[190:193], v[124:127]
	v_mfma_f32_16x16x32_bf16 v[120:123], v[166:169], v[190:193], v[120:123]
	v_mfma_f32_16x16x32_bf16 v[116:119], v[158:161], v[198:201], v[116:119]
	v_mfma_f32_16x16x32_bf16 v[112:115], v[166:169], v[198:201], v[112:115]
	v_mfma_f32_16x16x32_bf16 v[104:107], v[158:161], v[206:209], v[104:107]
	v_mfma_f32_16x16x32_bf16 v[96:99], v[166:169], v[206:209], v[96:99]
	v_mfma_f32_16x16x32_bf16 v[76:79], v[158:161], v[214:217], v[76:79]
	v_mfma_f32_16x16x32_bf16 v[72:75], v[166:169], v[214:217], v[72:75]
	v_mfma_f32_16x16x32_bf16 v[108:111], v[170:173], v[186:189], v[108:111]
	v_mfma_f32_16x16x32_bf16 v[100:103], v[178:181], v[186:189], v[100:103]
	v_mfma_f32_16x16x32_bf16 v[92:95], v[170:173], v[194:197], v[92:95]
	v_mfma_f32_16x16x32_bf16 v[88:91], v[178:181], v[194:197], v[88:91]
	v_mfma_f32_16x16x32_bf16 v[84:87], v[170:173], v[202:205], v[84:87]
	v_mfma_f32_16x16x32_bf16 v[80:83], v[178:181], v[202:205], v[80:83]
	v_mfma_f32_16x16x32_bf16 v[68:71], v[170:173], v[210:213], v[68:71]
	v_mfma_f32_16x16x32_bf16 v[64:67], v[178:181], v[210:213], v[64:67]
	v_mfma_f32_16x16x32_bf16 v[108:111], v[174:177], v[190:193], v[108:111]
	v_mfma_f32_16x16x32_bf16 v[100:103], v[182:185], v[190:193], v[100:103]
	v_mfma_f32_16x16x32_bf16 v[92:95], v[174:177], v[198:201], v[92:95]
	v_mfma_f32_16x16x32_bf16 v[88:91], v[182:185], v[198:201], v[88:91]
	v_mfma_f32_16x16x32_bf16 v[84:87], v[174:177], v[206:209], v[84:87]
	v_mfma_f32_16x16x32_bf16 v[80:83], v[182:185], v[206:209], v[80:83]
	v_mfma_f32_16x16x32_bf16 v[68:71], v[174:177], v[214:217], v[68:71]
	v_mfma_f32_16x16x32_bf16 v[64:67], v[182:185], v[214:217], v[64:67]
	s_barrier
	s_add_i32 s80, s63, s38
	s_mov_b32 m0, s80
	ds_read_b128 v[186:189], v151 offset:16384
	ds_read_b128 v[190:193], v151 offset:17408
	ds_read_b128 v[194:197], v151 offset:18432
	ds_read_b128 v[198:201], v151 offset:19456
	ds_read_b128 v[202:205], v151 offset:20480
	ds_read_b128 v[206:209], v151 offset:21504
	ds_read_b128 v[210:213], v151 offset:22528
	ds_read_b128 v[214:217], v151 offset:23552
	global_load_lds_dwordx4 v130, s[34:35]
	s_add_i32 m0, s80, 0x2000
	s_add_u32 s80, s34, 0x100000
	s_addc_u32 s81, s35, 0
	s_add_i32 s82, s68, s38
	global_load_lds_dwordx4 v134, s[34:35]
	s_mov_b32 m0, s82
	s_nop 0
	global_load_lds_dwordx4 v130, s[80:81]
	s_add_i32 m0, s82, 0x2000
	s_nop 0
	global_load_lds_dwordx4 v134, s[80:81]
	s_mov_b32 m0, s49
	s_nop 0
	global_load_lds_dwordx4 v128, s[36:37]
	s_mov_b32 m0, s54
	s_nop 0
	global_load_lds_dwordx4 v132, s[36:37]
	s_waitcnt vmcnt(8)
	s_waitcnt lgkmcnt(0)
	s_barrier
	s_waitcnt lgkmcnt(0)
	v_mfma_f32_16x16x32_bf16 v[60:63], v[154:157], v[186:189], v[60:63]
	v_mfma_f32_16x16x32_bf16 v[56:59], v[162:165], v[186:189], v[56:59]
	v_mfma_f32_16x16x32_bf16 v[44:47], v[154:157], v[194:197], v[44:47]
	v_mfma_f32_16x16x32_bf16 v[40:43], v[162:165], v[194:197], v[40:43]
	v_mfma_f32_16x16x32_bf16 v[28:31], v[154:157], v[202:205], v[28:31]
	v_mfma_f32_16x16x32_bf16 v[24:27], v[162:165], v[202:205], v[24:27]
	v_mfma_f32_16x16x32_bf16 v[12:15], v[154:157], v[210:213], v[12:15]
	v_mfma_f32_16x16x32_bf16 v[8:11], v[162:165], v[210:213], v[8:11]
	v_mfma_f32_16x16x32_bf16 v[60:63], v[158:161], v[190:193], v[60:63]
	v_mfma_f32_16x16x32_bf16 v[56:59], v[166:169], v[190:193], v[56:59]
	v_mfma_f32_16x16x32_bf16 v[44:47], v[158:161], v[198:201], v[44:47]
	v_mfma_f32_16x16x32_bf16 v[40:43], v[166:169], v[198:201], v[40:43]
	v_mfma_f32_16x16x32_bf16 v[28:31], v[158:161], v[206:209], v[28:31]
	v_mfma_f32_16x16x32_bf16 v[24:27], v[166:169], v[206:209], v[24:27]
	v_mfma_f32_16x16x32_bf16 v[12:15], v[158:161], v[214:217], v[12:15]
	v_mfma_f32_16x16x32_bf16 v[8:11], v[166:169], v[214:217], v[8:11]
	v_mfma_f32_16x16x32_bf16 v[52:55], v[170:173], v[186:189], v[52:55]
	v_mfma_f32_16x16x32_bf16 v[48:51], v[178:181], v[186:189], v[48:51]
	v_mfma_f32_16x16x32_bf16 v[36:39], v[170:173], v[194:197], v[36:39]
	v_mfma_f32_16x16x32_bf16 v[32:35], v[178:181], v[194:197], v[32:35]
	v_mfma_f32_16x16x32_bf16 v[20:23], v[170:173], v[202:205], v[20:23]
	v_mfma_f32_16x16x32_bf16 v[16:19], v[178:181], v[202:205], v[16:19]
	v_mfma_f32_16x16x32_bf16 v[4:7], v[170:173], v[210:213], v[4:7]
	v_mfma_f32_16x16x32_bf16 v[0:3], v[178:181], v[210:213], v[0:3]
	v_mfma_f32_16x16x32_bf16 v[52:55], v[174:177], v[190:193], v[52:55]
	v_mfma_f32_16x16x32_bf16 v[48:51], v[182:185], v[190:193], v[48:51]
	v_mfma_f32_16x16x32_bf16 v[36:39], v[174:177], v[198:201], v[36:39]
	v_mfma_f32_16x16x32_bf16 v[32:35], v[182:185], v[198:201], v[32:35]
	v_mfma_f32_16x16x32_bf16 v[20:23], v[174:177], v[206:209], v[20:23]
	v_mfma_f32_16x16x32_bf16 v[16:19], v[182:185], v[206:209], v[16:19]
	v_mfma_f32_16x16x32_bf16 v[4:7], v[174:177], v[214:217], v[4:7]
	v_mfma_f32_16x16x32_bf16 v[0:3], v[182:185], v[214:217], v[0:3]
	s_barrier
	s_add_i32 s80, 0, 0x18000
	s_add_i32 s81, 0, 0x1c000
	v_add_u32_e32 v166, s80, v147
	v_add_u32_e32 v182, s81, v147
	ds_read_b128 v[154:157], v166
	ds_read_b128 v[158:161], v166 offset:1024
	ds_read_b128 v[162:165], v166 offset:2048
	ds_read_b128 v[166:169], v166 offset:3072
	ds_read_b128 v[170:173], v182
	ds_read_b128 v[174:177], v182 offset:1024
	ds_read_b128 v[178:181], v182 offset:2048
	ds_read_b128 v[182:185], v182 offset:3072
	s_add_u32 s36, s36, 0x100000
	s_addc_u32 s37, s37, 0
	s_mov_b32 m0, s55
	ds_read_b128 v[186:189], v151 offset:32768
	ds_read_b128 v[190:193], v151 offset:33792
	ds_read_b128 v[194:197], v151 offset:34816
	ds_read_b128 v[198:201], v151 offset:35840
	ds_read_b128 v[202:205], v151 offset:36864
	ds_read_b128 v[206:209], v151 offset:37888
	ds_read_b128 v[210:213], v151 offset:38912
	ds_read_b128 v[214:217], v151 offset:39936
	global_load_lds_dwordx4 v128, s[36:37]
	s_mov_b32 m0, s56
	s_nop 0
	global_load_lds_dwordx4 v132, s[36:37]
	s_waitcnt vmcnt(8)
	s_waitcnt lgkmcnt(0)
	s_barrier
	s_waitcnt lgkmcnt(0)
	v_mfma_f32_16x16x32_bf16 v[124:127], v[154:157], v[186:189], v[124:127]
	v_mfma_f32_16x16x32_bf16 v[120:123], v[162:165], v[186:189], v[120:123]
	v_mfma_f32_16x16x32_bf16 v[116:119], v[154:157], v[194:197], v[116:119]
	v_mfma_f32_16x16x32_bf16 v[112:115], v[162:165], v[194:197], v[112:115]
	v_mfma_f32_16x16x32_bf16 v[104:107], v[154:157], v[202:205], v[104:107]
	v_mfma_f32_16x16x32_bf16 v[96:99], v[162:165], v[202:205], v[96:99]
	v_mfma_f32_16x16x32_bf16 v[76:79], v[154:157], v[210:213], v[76:79]
	v_mfma_f32_16x16x32_bf16 v[72:75], v[162:165], v[210:213], v[72:75]
	v_mfma_f32_16x16x32_bf16 v[124:127], v[158:161], v[190:193], v[124:127]
	v_mfma_f32_16x16x32_bf16 v[120:123], v[166:169], v[190:193], v[120:123]
	v_mfma_f32_16x16x32_bf16 v[116:119], v[158:161], v[198:201], v[116:119]
	v_mfma_f32_16x16x32_bf16 v[112:115], v[166:169], v[198:201], v[112:115]
	v_mfma_f32_16x16x32_bf16 v[104:107], v[158:161], v[206:209], v[104:107]
	v_mfma_f32_16x16x32_bf16 v[96:99], v[166:169], v[206:209], v[96:99]
	v_mfma_f32_16x16x32_bf16 v[76:79], v[158:161], v[214:217], v[76:79]
	v_mfma_f32_16x16x32_bf16 v[72:75], v[166:169], v[214:217], v[72:75]
	v_mfma_f32_16x16x32_bf16 v[108:111], v[170:173], v[186:189], v[108:111]
	v_mfma_f32_16x16x32_bf16 v[100:103], v[178:181], v[186:189], v[100:103]
	v_mfma_f32_16x16x32_bf16 v[92:95], v[170:173], v[194:197], v[92:95]
	v_mfma_f32_16x16x32_bf16 v[88:91], v[178:181], v[194:197], v[88:91]
	v_mfma_f32_16x16x32_bf16 v[84:87], v[170:173], v[202:205], v[84:87]
	v_mfma_f32_16x16x32_bf16 v[80:83], v[178:181], v[202:205], v[80:83]
	v_mfma_f32_16x16x32_bf16 v[68:71], v[170:173], v[210:213], v[68:71]
	v_mfma_f32_16x16x32_bf16 v[64:67], v[178:181], v[210:213], v[64:67]
	v_mfma_f32_16x16x32_bf16 v[108:111], v[174:177], v[190:193], v[108:111]
	v_mfma_f32_16x16x32_bf16 v[100:103], v[182:185], v[190:193], v[100:103]
	v_mfma_f32_16x16x32_bf16 v[92:95], v[174:177], v[198:201], v[92:95]
	v_mfma_f32_16x16x32_bf16 v[88:91], v[182:185], v[198:201], v[88:91]
	v_mfma_f32_16x16x32_bf16 v[84:87], v[174:177], v[206:209], v[84:87]
	v_mfma_f32_16x16x32_bf16 v[80:83], v[182:185], v[206:209], v[80:83]
	v_mfma_f32_16x16x32_bf16 v[68:71], v[174:177], v[214:217], v[68:71]
	v_mfma_f32_16x16x32_bf16 v[64:67], v[182:185], v[214:217], v[64:67]
	s_barrier
	s_add_i32 s36, s80, s38
	s_mov_b32 m0, s36
	ds_read_b128 v[186:189], v151 offset:49152
	ds_read_b128 v[190:193], v151 offset:50176
	ds_read_b128 v[194:197], v151 offset:51200
	ds_read_b128 v[198:201], v151 offset:52224
	ds_read_b128 v[202:205], v151 offset:53248
	ds_read_b128 v[206:209], v151 offset:54272
	ds_read_b128 v[210:213], v151 offset:55296
	ds_read_b128 v[214:217], v151 offset:56320
	global_load_lds_dwordx4 v130, s[98:99]
	s_add_i32 m0, s36, 0x2000
	s_add_u32 s34, s34, 0x100080
	s_addc_u32 s35, s35, 0
	s_add_i32 s36, s81, s38
	global_load_lds_dwordx4 v134, s[98:99]
	s_mov_b32 m0, s36
	s_nop 0
	global_load_lds_dwordx4 v130, s[34:35]
	s_add_i32 m0, s36, 0x2000
	s_nop 0
	global_load_lds_dwordx4 v134, s[34:35]
	s_mov_b32 m0, s58
	s_nop 0
	global_load_lds_dwordx4 v128, s[100:101]
	s_mov_b32 m0, s59
	s_nop 0
	global_load_lds_dwordx4 v132, s[100:101]
	s_waitcnt vmcnt(8)
	s_waitcnt lgkmcnt(0)
	s_barrier
	s_waitcnt lgkmcnt(0)
	v_mfma_f32_16x16x32_bf16 v[60:63], v[154:157], v[186:189], v[60:63]
	v_mfma_f32_16x16x32_bf16 v[56:59], v[162:165], v[186:189], v[56:59]
	v_mfma_f32_16x16x32_bf16 v[44:47], v[154:157], v[194:197], v[44:47]
	v_mfma_f32_16x16x32_bf16 v[40:43], v[162:165], v[194:197], v[40:43]
	v_mfma_f32_16x16x32_bf16 v[28:31], v[154:157], v[202:205], v[28:31]
	v_mfma_f32_16x16x32_bf16 v[24:27], v[162:165], v[202:205], v[24:27]
	v_mfma_f32_16x16x32_bf16 v[12:15], v[154:157], v[210:213], v[12:15]
	v_mfma_f32_16x16x32_bf16 v[8:11], v[162:165], v[210:213], v[8:11]
	v_mfma_f32_16x16x32_bf16 v[60:63], v[158:161], v[190:193], v[60:63]
	v_mfma_f32_16x16x32_bf16 v[56:59], v[166:169], v[190:193], v[56:59]
	v_mfma_f32_16x16x32_bf16 v[44:47], v[158:161], v[198:201], v[44:47]
	v_mfma_f32_16x16x32_bf16 v[40:43], v[166:169], v[198:201], v[40:43]
	v_mfma_f32_16x16x32_bf16 v[28:31], v[158:161], v[206:209], v[28:31]
	v_mfma_f32_16x16x32_bf16 v[24:27], v[166:169], v[206:209], v[24:27]
	v_mfma_f32_16x16x32_bf16 v[12:15], v[158:161], v[214:217], v[12:15]
	v_mfma_f32_16x16x32_bf16 v[8:11], v[166:169], v[214:217], v[8:11]
	v_mfma_f32_16x16x32_bf16 v[52:55], v[170:173], v[186:189], v[52:55]
	v_mfma_f32_16x16x32_bf16 v[48:51], v[178:181], v[186:189], v[48:51]
	v_mfma_f32_16x16x32_bf16 v[36:39], v[170:173], v[194:197], v[36:39]
	v_mfma_f32_16x16x32_bf16 v[32:35], v[178:181], v[194:197], v[32:35]
	v_mfma_f32_16x16x32_bf16 v[20:23], v[170:173], v[202:205], v[20:23]
	v_mfma_f32_16x16x32_bf16 v[16:19], v[178:181], v[202:205], v[16:19]
	v_mfma_f32_16x16x32_bf16 v[4:7], v[170:173], v[210:213], v[4:7]
	v_mfma_f32_16x16x32_bf16 v[0:3], v[178:181], v[210:213], v[0:3]
	v_mfma_f32_16x16x32_bf16 v[52:55], v[174:177], v[190:193], v[52:55]
	v_mfma_f32_16x16x32_bf16 v[48:51], v[182:185], v[190:193], v[48:51]
	v_mfma_f32_16x16x32_bf16 v[36:39], v[174:177], v[198:201], v[36:39]
	v_mfma_f32_16x16x32_bf16 v[32:35], v[182:185], v[198:201], v[32:35]
	v_mfma_f32_16x16x32_bf16 v[20:23], v[174:177], v[206:209], v[20:23]
	v_mfma_f32_16x16x32_bf16 v[16:19], v[182:185], v[206:209], v[16:19]
	v_mfma_f32_16x16x32_bf16 v[4:7], v[174:177], v[214:217], v[4:7]
	v_mfma_f32_16x16x32_bf16 v[0:3], v[182:185], v[214:217], v[0:3]
	s_barrier
	s_add_i32 s79, s79, 2
	s_add_u32 s30, s30, 0x100
	s_addc_u32 s31, s31, 0
	s_add_u32 s75, s75, 0x100
	s_addc_u32 s78, s78, 0
	s_cmp_gt_u32 s79, 61
	s_cbranch_scc0 .LBB0_188
	s_and_b64 vcc, exec, s[12:13]
	s_cbranch_vccz .LBB0_191
	s_barrier

.LBB0_431:
	ds_read_b128 v[128:131], v207
	ds_read_b128 v[132:135], v207 offset:1024
	ds_read_b128 v[136:139], v207 offset:2048
	ds_read_b128 v[140:143], v207 offset:3072
	ds_read_b128 v[144:147], v208
	ds_read_b128 v[148:151], v208 offset:1024
	ds_read_b128 v[152:155], v208 offset:2048
	ds_read_b128 v[156:159], v208 offset:3072
	s_add_u32 s28, s26, 0xfff00080
	s_addc_u32 s29, s27, -1
	s_cmp_eq_u32 s55, 60
	s_cselect_b32 s31, s15, s29
	s_cselect_b32 s30, s21, s28
	s_cselect_b32 s29, s13, s54
	s_cselect_b32 s28, s52, s53
	s_add_u32 s98, s28, s8
	s_addc_u32 s99, s29, s9
	s_add_u32 s100, s30, s8
	s_addc_u32 s101, s31, s9
	s_add_i32 m0, s23, 0xc000
	ds_read_b128 v[160:163], v209
	ds_read_b128 v[164:167], v209 offset:1024
	ds_read_b128 v[168:171], v209 offset:2048
	ds_read_b128 v[172:175], v209 offset:3072
	ds_read_b128 v[192:195], v209 offset:4096
	ds_read_b128 v[196:199], v209 offset:5120
	ds_read_b128 v[200:203], v209 offset:6144
	ds_read_b128 v[212:215], v209 offset:7168
	global_load_lds_dwordx4 v184, s[26:27]
	s_add_i32 m0, s23, 0xe000
	s_nop 0
	global_load_lds_dwordx4 v186, s[26:27]
	s_waitcnt vmcnt(8)
	s_waitcnt lgkmcnt(0)
	s_barrier
	s_waitcnt lgkmcnt(0)
	v_mfma_f32_16x16x32_bf16 v[124:127], v[128:131], v[160:163], v[124:127]
	v_mfma_f32_16x16x32_bf16 v[120:123], v[136:139], v[160:163], v[120:123]
	v_mfma_f32_16x16x32_bf16 v[108:111], v[128:131], v[168:171], v[108:111]
	v_mfma_f32_16x16x32_bf16 v[104:107], v[136:139], v[168:171], v[104:107]
	v_mfma_f32_16x16x32_bf16 v[92:95], v[128:131], v[192:195], v[92:95]
	v_mfma_f32_16x16x32_bf16 v[88:91], v[136:139], v[192:195], v[88:91]
	v_mfma_f32_16x16x32_bf16 v[76:79], v[128:131], v[200:203], v[76:79]
	v_mfma_f32_16x16x32_bf16 v[72:75], v[136:139], v[200:203], v[72:75]
	v_mfma_f32_16x16x32_bf16 v[124:127], v[132:135], v[164:167], v[124:127]
	v_mfma_f32_16x16x32_bf16 v[120:123], v[140:143], v[164:167], v[120:123]
	v_mfma_f32_16x16x32_bf16 v[108:111], v[132:135], v[172:175], v[108:111]
	v_mfma_f32_16x16x32_bf16 v[104:107], v[140:143], v[172:175], v[104:107]
	v_mfma_f32_16x16x32_bf16 v[92:95], v[132:135], v[196:199], v[92:95]
	v_mfma_f32_16x16x32_bf16 v[88:91], v[140:143], v[196:199], v[88:91]
	v_mfma_f32_16x16x32_bf16 v[76:79], v[132:135], v[212:215], v[76:79]
	v_mfma_f32_16x16x32_bf16 v[72:75], v[140:143], v[212:215], v[72:75]
	v_mfma_f32_16x16x32_bf16 v[116:119], v[144:147], v[160:163], v[116:119]
	v_mfma_f32_16x16x32_bf16 v[112:115], v[152:155], v[160:163], v[112:115]
	v_mfma_f32_16x16x32_bf16 v[100:103], v[144:147], v[168:171], v[100:103]
	v_mfma_f32_16x16x32_bf16 v[96:99], v[152:155], v[168:171], v[96:99]
	v_mfma_f32_16x16x32_bf16 v[84:87], v[144:147], v[192:195], v[84:87]
	v_mfma_f32_16x16x32_bf16 v[80:83], v[152:155], v[192:195], v[80:83]
	v_mfma_f32_16x16x32_bf16 v[68:71], v[144:147], v[200:203], v[68:71]
	v_mfma_f32_16x16x32_bf16 v[64:67], v[152:155], v[200:203], v[64:67]
	v_mfma_f32_16x16x32_bf16 v[116:119], v[148:151], v[164:167], v[116:119]
	v_mfma_f32_16x16x32_bf16 v[112:115], v[156:159], v[164:167], v[112:115]
	v_mfma_f32_16x16x32_bf16 v[100:103], v[148:151], v[172:175], v[100:103]
	v_mfma_f32_16x16x32_bf16 v[96:99], v[156:159], v[172:175], v[96:99]
	v_mfma_f32_16x16x32_bf16 v[84:87], v[148:151], v[196:199], v[84:87]
	v_mfma_f32_16x16x32_bf16 v[80:83], v[156:159], v[196:199], v[80:83]
	v_mfma_f32_16x16x32_bf16 v[68:71], v[148:151], v[212:215], v[68:71]
	v_mfma_f32_16x16x32_bf16 v[64:67], v[156:159], v[212:215], v[64:67]
	s_barrier
	s_add_i32 s58, s50, s3
	s_mov_b32 m0, s58
	ds_read_b128 v[160:163], v209 offset:16384
	ds_read_b128 v[164:167], v209 offset:17408
	ds_read_b128 v[168:171], v209 offset:18432
	ds_read_b128 v[172:175], v209 offset:19456
	ds_read_b128 v[192:195], v209 offset:20480
	ds_read_b128 v[196:199], v209 offset:21504
	ds_read_b128 v[200:203], v209 offset:22528
	ds_read_b128 v[212:215], v209 offset:23552
	global_load_lds_dwordx4 v178, s[28:29]
	s_add_i32 m0, s58, 0x2000
	s_add_u32 s58, s28, 0x100000
	s_addc_u32 s59, s29, 0
	s_add_i32 s62, s51, s3
	global_load_lds_dwordx4 v182, s[28:29]
	s_mov_b32 m0, s62
	s_nop 0
	global_load_lds_dwordx4 v178, s[58:59]
	s_add_i32 m0, s62, 0x2000
	s_nop 0
	global_load_lds_dwordx4 v182, s[58:59]
	s_mov_b32 m0, s23
	s_nop 0
	global_load_lds_dwordx4 v176, s[30:31]
	s_mov_b32 m0, s34
	s_nop 0
	global_load_lds_dwordx4 v180, s[30:31]
	s_waitcnt vmcnt(8)
	s_waitcnt lgkmcnt(0)
	s_barrier
	s_waitcnt lgkmcnt(0)
	v_mfma_f32_16x16x32_bf16 v[60:63], v[128:131], v[160:163], v[60:63]
	v_mfma_f32_16x16x32_bf16 v[56:59], v[136:139], v[160:163], v[56:59]
	v_mfma_f32_16x16x32_bf16 v[44:47], v[128:131], v[168:171], v[44:47]
	v_mfma_f32_16x16x32_bf16 v[40:43], v[136:139], v[168:171], v[40:43]
	v_mfma_f32_16x16x32_bf16 v[28:31], v[128:131], v[192:195], v[28:31]
	v_mfma_f32_16x16x32_bf16 v[24:27], v[136:139], v[192:195], v[24:27]
	v_mfma_f32_16x16x32_bf16 v[12:15], v[128:131], v[200:203], v[12:15]
	v_mfma_f32_16x16x32_bf16 v[8:11], v[136:139], v[200:203], v[8:11]
	v_mfma_f32_16x16x32_bf16 v[60:63], v[132:135], v[164:167], v[60:63]
	v_mfma_f32_16x16x32_bf16 v[56:59], v[140:143], v[164:167], v[56:59]
	v_mfma_f32_16x16x32_bf16 v[44:47], v[132:135], v[172:175], v[44:47]
	v_mfma_f32_16x16x32_bf16 v[40:43], v[140:143], v[172:175], v[40:43]
	v_mfma_f32_16x16x32_bf16 v[28:31], v[132:135], v[196:199], v[28:31]
	v_mfma_f32_16x16x32_bf16 v[24:27], v[140:143], v[196:199], v[24:27]
	v_mfma_f32_16x16x32_bf16 v[12:15], v[132:135], v[212:215], v[12:15]
	v_mfma_f32_16x16x32_bf16 v[8:11], v[140:143], v[212:215], v[8:11]
	v_mfma_f32_16x16x32_bf16 v[52:55], v[144:147], v[160:163], v[52:55]
	v_mfma_f32_16x16x32_bf16 v[48:51], v[152:155], v[160:163], v[48:51]
	v_mfma_f32_16x16x32_bf16 v[36:39], v[144:147], v[168:171], v[36:39]
	v_mfma_f32_16x16x32_bf16 v[32:35], v[152:155], v[168:171], v[32:35]
	v_mfma_f32_16x16x32_bf16 v[20:23], v[144:147], v[192:195], v[20:23]
	v_mfma_f32_16x16x32_bf16 v[16:19], v[152:155], v[192:195], v[16:19]
	v_mfma_f32_16x16x32_bf16 v[4:7], v[144:147], v[200:203], v[4:7]
	v_mfma_f32_16x16x32_bf16 v[0:3], v[152:155], v[200:203], v[0:3]
	v_mfma_f32_16x16x32_bf16 v[52:55], v[148:151], v[164:167], v[52:55]
	v_mfma_f32_16x16x32_bf16 v[48:51], v[156:159], v[164:167], v[48:51]
	v_mfma_f32_16x16x32_bf16 v[36:39], v[148:151], v[172:175], v[36:39]
	v_mfma_f32_16x16x32_bf16 v[32:35], v[156:159], v[172:175], v[32:35]
	v_mfma_f32_16x16x32_bf16 v[20:23], v[148:151], v[196:199], v[20:23]
	v_mfma_f32_16x16x32_bf16 v[16:19], v[156:159], v[196:199], v[16:19]
	v_mfma_f32_16x16x32_bf16 v[4:7], v[148:151], v[212:215], v[4:7]
	v_mfma_f32_16x16x32_bf16 v[0:3], v[156:159], v[212:215], v[0:3]
	s_barrier
	s_add_i32 s58, 0, 0x18000
	s_add_i32 s59, 0, 0x1c000
	v_add_u32_e32 v140, s58, v205
	v_add_u32_e32 v156, s59, v205
	ds_read_b128 v[128:131], v140
	ds_read_b128 v[132:135], v140 offset:1024
	ds_read_b128 v[136:139], v140 offset:2048
	ds_read_b128 v[140:143], v140 offset:3072
	ds_read_b128 v[144:147], v156
	ds_read_b128 v[148:151], v156 offset:1024
	ds_read_b128 v[152:155], v156 offset:2048
	ds_read_b128 v[156:159], v156 offset:3072
	s_add_u32 s30, s30, 0x100000
	s_addc_u32 s31, s31, 0
	s_mov_b32 m0, s35
	ds_read_b128 v[160:163], v209 offset:32768
	ds_read_b128 v[164:167], v209 offset:33792
	ds_read_b128 v[168:171], v209 offset:34816
	ds_read_b128 v[172:175], v209 offset:35840
	ds_read_b128 v[192:195], v209 offset:36864
	ds_read_b128 v[196:199], v209 offset:37888
	ds_read_b128 v[200:203], v209 offset:38912
	ds_read_b128 v[212:215], v209 offset:39936
	global_load_lds_dwordx4 v176, s[30:31]
	s_mov_b32 m0, s36
	s_nop 0
	global_load_lds_dwordx4 v180, s[30:31]
	s_waitcnt vmcnt(8)
	s_waitcnt lgkmcnt(0)
	s_barrier
	s_waitcnt lgkmcnt(0)
	v_mfma_f32_16x16x32_bf16 v[124:127], v[128:131], v[160:163], v[124:127]
	v_mfma_f32_16x16x32_bf16 v[120:123], v[136:139], v[160:163], v[120:123]
	v_mfma_f32_16x16x32_bf16 v[108:111], v[128:131], v[168:171], v[108:111]
	v_mfma_f32_16x16x32_bf16 v[104:107], v[136:139], v[168:171], v[104:107]
	v_mfma_f32_16x16x32_bf16 v[92:95], v[128:131], v[192:195], v[92:95]
	v_mfma_f32_16x16x32_bf16 v[88:91], v[136:139], v[192:195], v[88:91]
	v_mfma_f32_16x16x32_bf16 v[76:79], v[128:131], v[200:203], v[76:79]
	v_mfma_f32_16x16x32_bf16 v[72:75], v[136:139], v[200:203], v[72:75]
	v_mfma_f32_16x16x32_bf16 v[124:127], v[132:135], v[164:167], v[124:127]
	v_mfma_f32_16x16x32_bf16 v[120:123], v[140:143], v[164:167], v[120:123]
	v_mfma_f32_16x16x32_bf16 v[108:111], v[132:135], v[172:175], v[108:111]
	v_mfma_f32_16x16x32_bf16 v[104:107], v[140:143], v[172:175], v[104:107]
	v_mfma_f32_16x16x32_bf16 v[92:95], v[132:135], v[196:199], v[92:95]
	v_mfma_f32_16x16x32_bf16 v[88:91], v[140:143], v[196:199], v[88:91]
	v_mfma_f32_16x16x32_bf16 v[76:79], v[132:135], v[212:215], v[76:79]
	v_mfma_f32_16x16x32_bf16 v[72:75], v[140:143], v[212:215], v[72:75]
	v_mfma_f32_16x16x32_bf16 v[116:119], v[144:147], v[160:163], v[116:119]
	v_mfma_f32_16x16x32_bf16 v[112:115], v[152:155], v[160:163], v[112:115]
	v_mfma_f32_16x16x32_bf16 v[100:103], v[144:147], v[168:171], v[100:103]
	v_mfma_f32_16x16x32_bf16 v[96:99], v[152:155], v[168:171], v[96:99]
	v_mfma_f32_16x16x32_bf16 v[84:87], v[144:147], v[192:195], v[84:87]
	v_mfma_f32_16x16x32_bf16 v[80:83], v[152:155], v[192:195], v[80:83]
	v_mfma_f32_16x16x32_bf16 v[68:71], v[144:147], v[200:203], v[68:71]
	v_mfma_f32_16x16x32_bf16 v[64:67], v[152:155], v[200:203], v[64:67]
	v_mfma_f32_16x16x32_bf16 v[116:119], v[148:151], v[164:167], v[116:119]
	v_mfma_f32_16x16x32_bf16 v[112:115], v[156:159], v[164:167], v[112:115]
	v_mfma_f32_16x16x32_bf16 v[100:103], v[148:151], v[172:175], v[100:103]
	v_mfma_f32_16x16x32_bf16 v[96:99], v[156:159], v[172:175], v[96:99]
	v_mfma_f32_16x16x32_bf16 v[84:87], v[148:151], v[196:199], v[84:87]
	v_mfma_f32_16x16x32_bf16 v[80:83], v[156:159], v[196:199], v[80:83]
	v_mfma_f32_16x16x32_bf16 v[68:71], v[148:151], v[212:215], v[68:71]
	v_mfma_f32_16x16x32_bf16 v[64:67], v[156:159], v[212:215], v[64:67]
	s_barrier
	s_add_i32 s30, s58, s3
	s_mov_b32 m0, s30
	ds_read_b128 v[160:163], v209 offset:49152
	ds_read_b128 v[164:167], v209 offset:50176
	ds_read_b128 v[168:171], v209 offset:51200
	ds_read_b128 v[172:175], v209 offset:52224
	ds_read_b128 v[192:195], v209 offset:53248
	ds_read_b128 v[196:199], v209 offset:54272
	ds_read_b128 v[200:203], v209 offset:55296
	ds_read_b128 v[212:215], v209 offset:56320
	global_load_lds_dwordx4 v178, s[98:99]
	s_add_i32 m0, s30, 0x2000
	s_add_u32 s28, s28, 0x100080
	s_addc_u32 s29, s29, 0
	s_add_i32 s30, s59, s3
	global_load_lds_dwordx4 v182, s[98:99]
	s_mov_b32 m0, s30
	s_nop 0
	global_load_lds_dwordx4 v178, s[28:29]
	s_add_i32 m0, s30, 0x2000
	s_nop 0
	global_load_lds_dwordx4 v182, s[28:29]
	s_mov_b32 m0, s38
	s_nop 0
	global_load_lds_dwordx4 v176, s[100:101]
	s_mov_b32 m0, s39
	s_nop 0
	global_load_lds_dwordx4 v180, s[100:101]
	s_waitcnt vmcnt(8)
	s_waitcnt lgkmcnt(0)
	s_barrier
	s_waitcnt lgkmcnt(0)
	v_mfma_f32_16x16x32_bf16 v[60:63], v[128:131], v[160:163], v[60:63]
	v_mfma_f32_16x16x32_bf16 v[56:59], v[136:139], v[160:163], v[56:59]
	v_mfma_f32_16x16x32_bf16 v[44:47], v[128:131], v[168:171], v[44:47]
	v_mfma_f32_16x16x32_bf16 v[40:43], v[136:139], v[168:171], v[40:43]
	v_mfma_f32_16x16x32_bf16 v[28:31], v[128:131], v[192:195], v[28:31]
	v_mfma_f32_16x16x32_bf16 v[24:27], v[136:139], v[192:195], v[24:27]
	v_mfma_f32_16x16x32_bf16 v[12:15], v[128:131], v[200:203], v[12:15]
	v_mfma_f32_16x16x32_bf16 v[8:11], v[136:139], v[200:203], v[8:11]
	v_mfma_f32_16x16x32_bf16 v[60:63], v[132:135], v[164:167], v[60:63]
	v_mfma_f32_16x16x32_bf16 v[56:59], v[140:143], v[164:167], v[56:59]
	v_mfma_f32_16x16x32_bf16 v[44:47], v[132:135], v[172:175], v[44:47]
	v_mfma_f32_16x16x32_bf16 v[40:43], v[140:143], v[172:175], v[40:43]
	v_mfma_f32_16x16x32_bf16 v[28:31], v[132:135], v[196:199], v[28:31]
	v_mfma_f32_16x16x32_bf16 v[24:27], v[140:143], v[196:199], v[24:27]
	v_mfma_f32_16x16x32_bf16 v[12:15], v[132:135], v[212:215], v[12:15]
	v_mfma_f32_16x16x32_bf16 v[8:11], v[140:143], v[212:215], v[8:11]
	v_mfma_f32_16x16x32_bf16 v[52:55], v[144:147], v[160:163], v[52:55]
	v_mfma_f32_16x16x32_bf16 v[48:51], v[152:155], v[160:163], v[48:51]
	v_mfma_f32_16x16x32_bf16 v[36:39], v[144:147], v[168:171], v[36:39]
	v_mfma_f32_16x16x32_bf16 v[32:35], v[152:155], v[168:171], v[32:35]
	v_mfma_f32_16x16x32_bf16 v[20:23], v[144:147], v[192:195], v[20:23]
	v_mfma_f32_16x16x32_bf16 v[16:19], v[152:155], v[192:195], v[16:19]
	v_mfma_f32_16x16x32_bf16 v[4:7], v[144:147], v[200:203], v[4:7]
	v_mfma_f32_16x16x32_bf16 v[0:3], v[152:155], v[200:203], v[0:3]
	v_mfma_f32_16x16x32_bf16 v[52:55], v[148:151], v[164:167], v[52:55]
	v_mfma_f32_16x16x32_bf16 v[48:51], v[156:159], v[164:167], v[48:51]
	v_mfma_f32_16x16x32_bf16 v[36:39], v[148:151], v[172:175], v[36:39]
	v_mfma_f32_16x16x32_bf16 v[32:35], v[156:159], v[172:175], v[32:35]
	v_mfma_f32_16x16x32_bf16 v[20:23], v[148:151], v[196:199], v[20:23]
	v_mfma_f32_16x16x32_bf16 v[16:19], v[156:159], v[196:199], v[16:19]
	v_mfma_f32_16x16x32_bf16 v[4:7], v[148:151], v[212:215], v[4:7]
	v_mfma_f32_16x16x32_bf16 v[0:3], v[156:159], v[212:215], v[0:3]
	s_barrier
	s_add_i32 s55, s55, 2
	s_add_u32 s26, s26, 0x100
	s_addc_u32 s27, s27, 0
	s_add_u32 s53, s53, 0x100
	s_addc_u32 s54, s54, 0
	s_cmp_gt_u32 s55, 61
	s_cbranch_scc0 .LBB0_431
	s_and_b64 vcc, exec, s[10:11]
	s_cbranch_vccz .LBB0_434
	s_barrier

.LBB0_528:
	ds_read_b128 v[134:137], v200
	ds_read_b128 v[138:141], v200 offset:1024
	ds_read_b128 v[162:165], v200 offset:2048
	ds_read_b128 v[166:169], v200 offset:3072
	ds_read_b128 v[170:173], v201
	ds_read_b128 v[174:177], v201 offset:1024
	ds_read_b128 v[178:181], v201 offset:2048
	ds_read_b128 v[206:209], v201 offset:3072
	s_add_u32 s62, s20, 0xfff00080
	s_addc_u32 s63, s21, -1
	s_cmp_eq_u32 s83, 60
	s_cselect_b32 s79, s47, s63
	s_cselect_b32 s78, s57, s62
	s_cselect_b32 s63, s41, s82
	s_cselect_b32 s62, s59, s81
	s_add_u32 s98, s62, s30
	s_addc_u32 s99, s63, s31
	s_add_u32 s100, s78, s30
	s_addc_u32 s101, s79, s31
	s_add_i32 m0, s39, 0xc000
	ds_read_b128 v[210:213], v202
	ds_read_b128 v[214:217], v202 offset:1024
	ds_read_b128 v[218:221], v202 offset:2048
	ds_read_b128 v[222:225], v202 offset:3072
	ds_read_b128 v[226:229], v202 offset:4096
	ds_read_b128 v[230:233], v202 offset:5120
	ds_read_b128 v[234:237], v202 offset:6144
	ds_read_b128 v[238:241], v202 offset:7168
	global_load_lds_dwordx4 v154, s[20:21]
	s_add_i32 m0, s39, 0xe000
	s_nop 0
	global_load_lds_dwordx4 v156, s[20:21]
	s_waitcnt vmcnt(8)
	s_waitcnt lgkmcnt(0)
	s_barrier
	s_waitcnt lgkmcnt(0)
	v_mfma_f32_16x16x32_bf16 v[130:133], v[210:213], v[134:137], v[130:133]
	v_mfma_f32_16x16x32_bf16 v[126:129], v[210:213], v[162:165], v[126:129]
	v_mfma_f32_16x16x32_bf16 v[122:125], v[218:221], v[134:137], v[122:125]
	v_mfma_f32_16x16x32_bf16 v[118:121], v[218:221], v[162:165], v[118:121]
	v_mfma_f32_16x16x32_bf16 v[114:117], v[226:229], v[134:137], v[114:117]
	v_mfma_f32_16x16x32_bf16 v[110:113], v[226:229], v[162:165], v[110:113]
	v_mfma_f32_16x16x32_bf16 v[106:109], v[234:237], v[134:137], v[106:109]
	v_mfma_f32_16x16x32_bf16 v[102:105], v[234:237], v[162:165], v[102:105]
	v_mfma_f32_16x16x32_bf16 v[130:133], v[214:217], v[138:141], v[130:133]
	v_mfma_f32_16x16x32_bf16 v[126:129], v[214:217], v[166:169], v[126:129]
	v_mfma_f32_16x16x32_bf16 v[122:125], v[222:225], v[138:141], v[122:125]
	v_mfma_f32_16x16x32_bf16 v[118:121], v[222:225], v[166:169], v[118:121]
	v_mfma_f32_16x16x32_bf16 v[114:117], v[230:233], v[138:141], v[114:117]
	v_mfma_f32_16x16x32_bf16 v[110:113], v[230:233], v[166:169], v[110:113]
	v_mfma_f32_16x16x32_bf16 v[106:109], v[238:241], v[138:141], v[106:109]
	v_mfma_f32_16x16x32_bf16 v[102:105], v[238:241], v[166:169], v[102:105]
	v_mfma_f32_16x16x32_bf16 v[64:67], v[170:173], v[210:213], v[64:67]
	v_mfma_f32_16x16x32_bf16 v[60:63], v[178:181], v[210:213], v[60:63]
	v_mfma_f32_16x16x32_bf16 v[56:59], v[170:173], v[218:221], v[56:59]
	v_mfma_f32_16x16x32_bf16 v[52:55], v[178:181], v[218:221], v[52:55]
	v_mfma_f32_16x16x32_bf16 v[48:51], v[170:173], v[226:229], v[48:51]
	v_mfma_f32_16x16x32_bf16 v[44:47], v[178:181], v[226:229], v[44:47]
	v_mfma_f32_16x16x32_bf16 v[40:43], v[170:173], v[234:237], v[40:43]
	v_mfma_f32_16x16x32_bf16 v[36:39], v[178:181], v[234:237], v[36:39]
	v_mfma_f32_16x16x32_bf16 v[64:67], v[174:177], v[214:217], v[64:67]
	v_mfma_f32_16x16x32_bf16 v[60:63], v[206:209], v[214:217], v[60:63]
	v_mfma_f32_16x16x32_bf16 v[56:59], v[174:177], v[222:225], v[56:59]
	v_mfma_f32_16x16x32_bf16 v[52:55], v[206:209], v[222:225], v[52:55]
	v_mfma_f32_16x16x32_bf16 v[48:51], v[174:177], v[230:233], v[48:51]
	v_mfma_f32_16x16x32_bf16 v[44:47], v[206:209], v[230:233], v[44:47]
	v_mfma_f32_16x16x32_bf16 v[40:43], v[174:177], v[238:241], v[40:43]
	v_mfma_f32_16x16x32_bf16 v[36:39], v[206:209], v[238:241], v[36:39]
	s_barrier
	s_add_i32 s84, s75, s3
	s_mov_b32 m0, s84
	ds_read_b128 v[210:213], v202 offset:16384
	ds_read_b128 v[214:217], v202 offset:17408
	ds_read_b128 v[218:221], v202 offset:18432
	ds_read_b128 v[222:225], v202 offset:19456
	ds_read_b128 v[226:229], v202 offset:20480
	ds_read_b128 v[230:233], v202 offset:21504
	ds_read_b128 v[234:237], v202 offset:22528
	ds_read_b128 v[238:241], v202 offset:23552
	global_load_lds_dwordx4 v144, s[62:63]
	s_add_i32 m0, s84, 0x2000
	s_add_u32 s84, s62, 0x100000
	s_addc_u32 s85, s63, 0
	s_add_i32 s86, s80, s3
	global_load_lds_dwordx4 v148, s[62:63]
	s_mov_b32 m0, s86
	s_nop 0
	global_load_lds_dwordx4 v144, s[84:85]
	s_add_i32 m0, s86, 0x2000
	s_nop 0
	global_load_lds_dwordx4 v148, s[84:85]
	s_mov_b32 m0, s39
	s_nop 0
	global_load_lds_dwordx4 v142, s[78:79]
	s_mov_b32 m0, s54
	s_nop 0
	global_load_lds_dwordx4 v146, s[78:79]
	s_waitcnt vmcnt(8)
	s_waitcnt lgkmcnt(0)
	s_barrier
	s_waitcnt lgkmcnt(0)
	v_mfma_f32_16x16x32_bf16 v[98:101], v[210:213], v[134:137], v[98:101]
	v_mfma_f32_16x16x32_bf16 v[94:97], v[210:213], v[162:165], v[94:97]
	v_mfma_f32_16x16x32_bf16 v[90:93], v[218:221], v[134:137], v[90:93]
	v_mfma_f32_16x16x32_bf16 v[86:89], v[218:221], v[162:165], v[86:89]
	v_mfma_f32_16x16x32_bf16 v[82:85], v[226:229], v[134:137], v[82:85]
	v_mfma_f32_16x16x32_bf16 v[68:71], v[226:229], v[162:165], v[68:71]
	v_mfma_f32_16x16x32_bf16 v[72:75], v[234:237], v[134:137], v[74:77]
	v_mfma_f32_16x16x32_bf16 v[76:79], v[234:237], v[162:165], v[78:81]
	v_mfma_f32_16x16x32_bf16 v[98:101], v[214:217], v[138:141], v[98:101]
	v_mfma_f32_16x16x32_bf16 v[94:97], v[214:217], v[166:169], v[94:97]
	v_mfma_f32_16x16x32_bf16 v[90:93], v[222:225], v[138:141], v[90:93]
	v_mfma_f32_16x16x32_bf16 v[86:89], v[222:225], v[166:169], v[86:89]
	v_mfma_f32_16x16x32_bf16 v[82:85], v[230:233], v[138:141], v[82:85]
	v_mfma_f32_16x16x32_bf16 v[68:71], v[230:233], v[166:169], v[68:71]
	v_mfma_f32_16x16x32_bf16 v[72:75], v[238:241], v[138:141], v[72:75]
	v_mfma_f32_16x16x32_bf16 v[78:81], v[238:241], v[166:169], v[76:79]
	v_mfma_f32_16x16x32_bf16 v[32:35], v[170:173], v[210:213], v[32:35]
	v_mfma_f32_16x16x32_bf16 v[28:31], v[178:181], v[210:213], v[28:31]
	v_mfma_f32_16x16x32_bf16 v[24:27], v[170:173], v[218:221], v[24:27]
	v_mfma_f32_16x16x32_bf16 v[20:23], v[178:181], v[218:221], v[20:23]
	v_mfma_f32_16x16x32_bf16 v[16:19], v[170:173], v[226:229], v[16:19]
	v_mfma_f32_16x16x32_bf16 v[12:15], v[178:181], v[226:229], v[12:15]
	v_mfma_f32_16x16x32_bf16 v[2:5], v[170:173], v[234:237], v[4:7]
	v_mfma_f32_16x16x32_bf16 v[6:9], v[178:181], v[234:237], v[8:11]
	v_mfma_f32_16x16x32_bf16 v[32:35], v[174:177], v[214:217], v[32:35]
	v_mfma_f32_16x16x32_bf16 v[28:31], v[206:209], v[214:217], v[28:31]
	v_mfma_f32_16x16x32_bf16 v[24:27], v[174:177], v[222:225], v[24:27]
	v_mfma_f32_16x16x32_bf16 v[20:23], v[206:209], v[222:225], v[20:23]
	v_mfma_f32_16x16x32_bf16 v[16:19], v[174:177], v[230:233], v[16:19]
	v_mfma_f32_16x16x32_bf16 v[12:15], v[206:209], v[230:233], v[12:15]
	v_mfma_f32_16x16x32_bf16 v[2:5], v[174:177], v[238:241], v[2:5]
	v_mfma_f32_16x16x32_bf16 v[8:11], v[206:209], v[238:241], v[6:9]
	s_barrier
	s_add_i32 s84, 0, 0x18000
	v_add_u32_e32 v1, s84, v183
	s_add_i32 s85, 0, 0x1c000
	ds_read_b128 v[134:137], v1
	ds_read_b128 v[138:141], v1 offset:1024
	ds_read_b128 v[162:165], v1 offset:2048
	ds_read_b128 v[166:169], v1 offset:3072
	v_add_u32_e32 v1, s85, v183
	ds_read_b128 v[170:173], v1
	ds_read_b128 v[174:177], v1 offset:1024
	ds_read_b128 v[178:181], v1 offset:2048
	ds_read_b128 v[206:209], v1 offset:3072
	s_add_u32 s78, s78, 0x100000
	s_addc_u32 s79, s79, 0
	s_mov_b32 m0, s55
	ds_read_b128 v[210:213], v202 offset:32768
	ds_read_b128 v[214:217], v202 offset:33792
	ds_read_b128 v[218:221], v202 offset:34816
	ds_read_b128 v[222:225], v202 offset:35840
	ds_read_b128 v[226:229], v202 offset:36864
	ds_read_b128 v[230:233], v202 offset:37888
	ds_read_b128 v[234:237], v202 offset:38912
	ds_read_b128 v[238:241], v202 offset:39936
	global_load_lds_dwordx4 v142, s[78:79]
	s_mov_b32 m0, s68
	s_nop 0
	global_load_lds_dwordx4 v146, s[78:79]
	s_waitcnt vmcnt(8)
	s_waitcnt lgkmcnt(0)
	s_barrier
	s_waitcnt lgkmcnt(0)
	v_mfma_f32_16x16x32_bf16 v[130:133], v[210:213], v[134:137], v[130:133]
	v_mfma_f32_16x16x32_bf16 v[126:129], v[210:213], v[162:165], v[126:129]
	v_mfma_f32_16x16x32_bf16 v[122:125], v[218:221], v[134:137], v[122:125]
	v_mfma_f32_16x16x32_bf16 v[118:121], v[218:221], v[162:165], v[118:121]
	v_mfma_f32_16x16x32_bf16 v[114:117], v[226:229], v[134:137], v[114:117]
	v_mfma_f32_16x16x32_bf16 v[110:113], v[226:229], v[162:165], v[110:113]
	v_mfma_f32_16x16x32_bf16 v[106:109], v[234:237], v[134:137], v[106:109]
	v_mfma_f32_16x16x32_bf16 v[102:105], v[234:237], v[162:165], v[102:105]
	v_mfma_f32_16x16x32_bf16 v[130:133], v[214:217], v[138:141], v[130:133]
	v_mfma_f32_16x16x32_bf16 v[126:129], v[214:217], v[166:169], v[126:129]
	v_mfma_f32_16x16x32_bf16 v[122:125], v[222:225], v[138:141], v[122:125]
	v_mfma_f32_16x16x32_bf16 v[118:121], v[222:225], v[166:169], v[118:121]
	v_mfma_f32_16x16x32_bf16 v[114:117], v[230:233], v[138:141], v[114:117]
	v_mfma_f32_16x16x32_bf16 v[110:113], v[230:233], v[166:169], v[110:113]
	v_mfma_f32_16x16x32_bf16 v[106:109], v[238:241], v[138:141], v[106:109]
	v_mfma_f32_16x16x32_bf16 v[102:105], v[238:241], v[166:169], v[102:105]
	v_mfma_f32_16x16x32_bf16 v[64:67], v[170:173], v[210:213], v[64:67]
	v_mfma_f32_16x16x32_bf16 v[60:63], v[178:181], v[210:213], v[60:63]
	v_mfma_f32_16x16x32_bf16 v[56:59], v[170:173], v[218:221], v[56:59]
	v_mfma_f32_16x16x32_bf16 v[52:55], v[178:181], v[218:221], v[52:55]
	v_mfma_f32_16x16x32_bf16 v[48:51], v[170:173], v[226:229], v[48:51]
	v_mfma_f32_16x16x32_bf16 v[44:47], v[178:181], v[226:229], v[44:47]
	v_mfma_f32_16x16x32_bf16 v[40:43], v[170:173], v[234:237], v[40:43]
	v_mfma_f32_16x16x32_bf16 v[36:39], v[178:181], v[234:237], v[36:39]
	v_mfma_f32_16x16x32_bf16 v[64:67], v[174:177], v[214:217], v[64:67]
	v_mfma_f32_16x16x32_bf16 v[60:63], v[206:209], v[214:217], v[60:63]
	v_mfma_f32_16x16x32_bf16 v[56:59], v[174:177], v[222:225], v[56:59]
	v_mfma_f32_16x16x32_bf16 v[52:55], v[206:209], v[222:225], v[52:55]
	v_mfma_f32_16x16x32_bf16 v[48:51], v[174:177], v[230:233], v[48:51]
	v_mfma_f32_16x16x32_bf16 v[44:47], v[206:209], v[230:233], v[44:47]
	v_mfma_f32_16x16x32_bf16 v[40:43], v[174:177], v[238:241], v[40:43]
	v_mfma_f32_16x16x32_bf16 v[36:39], v[206:209], v[238:241], v[36:39]
	s_barrier
	s_add_i32 s78, s84, s3
	s_mov_b32 m0, s78
	ds_read_b128 v[210:213], v202 offset:49152
	ds_read_b128 v[214:217], v202 offset:50176
	ds_read_b128 v[218:221], v202 offset:51200
	ds_read_b128 v[222:225], v202 offset:52224
	ds_read_b128 v[226:229], v202 offset:53248
	ds_read_b128 v[230:233], v202 offset:54272
	ds_read_b128 v[234:237], v202 offset:55296
	ds_read_b128 v[238:241], v202 offset:56320
	global_load_lds_dwordx4 v144, s[98:99]
	s_add_i32 m0, s78, 0x2000
	s_add_u32 s62, s62, 0x100080
	s_addc_u32 s63, s63, 0
	s_add_i32 s78, s85, s3
	global_load_lds_dwordx4 v148, s[98:99]
	s_mov_b32 m0, s78
	s_nop 0
	global_load_lds_dwordx4 v144, s[62:63]
	s_add_i32 m0, s78, 0x2000
	s_nop 0
	global_load_lds_dwordx4 v148, s[62:63]
	s_mov_b32 m0, s71
	s_nop 0
	global_load_lds_dwordx4 v142, s[100:101]
	s_mov_b32 m0, s72
	s_nop 0
	global_load_lds_dwordx4 v146, s[100:101]
	s_waitcnt vmcnt(8)
	s_waitcnt lgkmcnt(0)
	s_barrier
	s_waitcnt lgkmcnt(0)
	v_mfma_f32_16x16x32_bf16 v[98:101], v[210:213], v[134:137], v[98:101]
	v_mfma_f32_16x16x32_bf16 v[94:97], v[210:213], v[162:165], v[94:97]
	v_mfma_f32_16x16x32_bf16 v[90:93], v[218:221], v[134:137], v[90:93]
	v_mfma_f32_16x16x32_bf16 v[86:89], v[218:221], v[162:165], v[86:89]
	v_mfma_f32_16x16x32_bf16 v[82:85], v[226:229], v[134:137], v[82:85]
	v_mfma_f32_16x16x32_bf16 v[68:71], v[226:229], v[162:165], v[68:71]
	v_mfma_f32_16x16x32_bf16 v[72:75], v[234:237], v[134:137], v[72:75]
	v_mfma_f32_16x16x32_bf16 v[78:81], v[234:237], v[162:165], v[78:81]
	v_mfma_f32_16x16x32_bf16 v[98:101], v[214:217], v[138:141], v[98:101]
	v_mfma_f32_16x16x32_bf16 v[94:97], v[214:217], v[166:169], v[94:97]
	v_mfma_f32_16x16x32_bf16 v[90:93], v[222:225], v[138:141], v[90:93]
	v_mfma_f32_16x16x32_bf16 v[86:89], v[222:225], v[166:169], v[86:89]
	v_mfma_f32_16x16x32_bf16 v[82:85], v[230:233], v[138:141], v[82:85]
	v_mfma_f32_16x16x32_bf16 v[68:71], v[230:233], v[166:169], v[68:71]
	v_mfma_f32_16x16x32_bf16 v[74:77], v[238:241], v[138:141], v[72:75]
	v_mfma_f32_16x16x32_bf16 v[78:81], v[238:241], v[166:169], v[78:81]
	v_mfma_f32_16x16x32_bf16 v[32:35], v[170:173], v[210:213], v[32:35]
	v_mfma_f32_16x16x32_bf16 v[28:31], v[178:181], v[210:213], v[28:31]
	v_mfma_f32_16x16x32_bf16 v[24:27], v[170:173], v[218:221], v[24:27]
	v_mfma_f32_16x16x32_bf16 v[20:23], v[178:181], v[218:221], v[20:23]
	v_mfma_f32_16x16x32_bf16 v[16:19], v[170:173], v[226:229], v[16:19]
	v_mfma_f32_16x16x32_bf16 v[12:15], v[178:181], v[226:229], v[12:15]
	v_mfma_f32_16x16x32_bf16 v[2:5], v[170:173], v[234:237], v[2:5]
	v_mfma_f32_16x16x32_bf16 v[8:11], v[178:181], v[234:237], v[8:11]
	v_mfma_f32_16x16x32_bf16 v[32:35], v[174:177], v[214:217], v[32:35]
	v_mfma_f32_16x16x32_bf16 v[28:31], v[206:209], v[214:217], v[28:31]
	v_mfma_f32_16x16x32_bf16 v[24:27], v[174:177], v[222:225], v[24:27]
	v_mfma_f32_16x16x32_bf16 v[20:23], v[206:209], v[222:225], v[20:23]
	v_mfma_f32_16x16x32_bf16 v[16:19], v[174:177], v[230:233], v[16:19]
	v_mfma_f32_16x16x32_bf16 v[12:15], v[206:209], v[230:233], v[12:15]
	v_mfma_f32_16x16x32_bf16 v[4:7], v[174:177], v[238:241], v[2:5]
	v_mfma_f32_16x16x32_bf16 v[8:11], v[206:209], v[238:241], v[8:11]
	s_barrier
	s_add_i32 s83, s83, 2
	s_add_u32 s20, s20, 0x100
	s_addc_u32 s21, s21, 0
	s_add_u32 s81, s81, 0x100
	s_addc_u32 s82, s82, 0
	s_cmp_gt_u32 s83, 61
	s_cbranch_scc0 .LBB0_528
	s_and_b64 vcc, exec, s[34:35]
	s_cbranch_vccz .LBB0_531
	s_barrier

.LBB0_815:
	ds_read_b128 v[56:59], v241
	ds_read_b128 v[60:63], v241 offset:1024
	ds_read_b128 v[64:67], v241 offset:2048
	ds_read_b128 v[68:71], v241 offset:3072
	ds_read_b128 v[144:147], v242
	ds_read_b128 v[148:151], v242 offset:1024
	ds_read_b128 v[152:155], v242 offset:2048
	ds_read_b128 v[156:159], v242 offset:3072
	s_add_u32 s50, s46, 0xffe00080
	s_addc_u32 s51, s47, -1
	s_cmpk_eq_i32 s77, 0x7c
	s_cselect_b32 s53, s29, s51
	s_cselect_b32 s52, s39, s50
	s_cselect_b32 s51, s31, s76
	s_cselect_b32 s50, s41, s75
	s_add_u32 s98, s50, s12
	s_addc_u32 s99, s51, s13
	s_add_u32 s100, s52, s12
	s_addc_u32 s101, s53, s13
	s_add_i32 m0, s55, 0xc000
	ds_read_b128 v[160:163], v243
	ds_read_b128 v[164:167], v243 offset:1024
	ds_read_b128 v[168:171], v243 offset:2048
	ds_read_b128 v[172:175], v243 offset:3072
	ds_read_b128 v[176:179], v243 offset:4096
	ds_read_b128 v[180:183], v243 offset:5120
	ds_read_b128 v[184:187], v243 offset:6144
	ds_read_b128 v[188:191], v243 offset:7168
	global_load_lds_dwordx4 v216, s[46:47]
	s_add_i32 m0, s55, 0xe000
	s_nop 0
	global_load_lds_dwordx4 v218, s[46:47]
	s_waitcnt vmcnt(8)
	s_waitcnt lgkmcnt(0)
	s_barrier
	s_waitcnt lgkmcnt(0)
	v_mfma_f32_16x16x32_bf16 v[140:143], v[56:59], v[160:163], v[140:143]
	v_mfma_f32_16x16x32_bf16 v[136:139], v[64:67], v[160:163], v[136:139]
	v_mfma_f32_16x16x32_bf16 v[124:127], v[56:59], v[168:171], v[124:127]
	v_mfma_f32_16x16x32_bf16 v[120:123], v[64:67], v[168:171], v[120:123]
	v_mfma_f32_16x16x32_bf16 v[108:111], v[56:59], v[176:179], v[108:111]
	v_mfma_f32_16x16x32_bf16 v[104:107], v[64:67], v[176:179], v[104:107]
	v_mfma_f32_16x16x32_bf16 v[92:95], v[56:59], v[184:187], v[92:95]
	v_mfma_f32_16x16x32_bf16 v[88:91], v[64:67], v[184:187], v[88:91]
	v_mfma_f32_16x16x32_bf16 v[140:143], v[60:63], v[164:167], v[140:143]
	v_mfma_f32_16x16x32_bf16 v[136:139], v[68:71], v[164:167], v[136:139]
	v_mfma_f32_16x16x32_bf16 v[124:127], v[60:63], v[172:175], v[124:127]
	v_mfma_f32_16x16x32_bf16 v[120:123], v[68:71], v[172:175], v[120:123]
	v_mfma_f32_16x16x32_bf16 v[108:111], v[60:63], v[180:183], v[108:111]
	v_mfma_f32_16x16x32_bf16 v[104:107], v[68:71], v[180:183], v[104:107]
	v_mfma_f32_16x16x32_bf16 v[92:95], v[60:63], v[188:191], v[92:95]
	v_mfma_f32_16x16x32_bf16 v[88:91], v[68:71], v[188:191], v[88:91]
	v_mfma_f32_16x16x32_bf16 v[132:135], v[144:147], v[160:163], v[132:135]
	v_mfma_f32_16x16x32_bf16 v[128:131], v[152:155], v[160:163], v[128:131]
	v_mfma_f32_16x16x32_bf16 v[116:119], v[144:147], v[168:171], v[116:119]
	v_mfma_f32_16x16x32_bf16 v[112:115], v[152:155], v[168:171], v[112:115]
	v_mfma_f32_16x16x32_bf16 v[100:103], v[144:147], v[176:179], v[100:103]
	v_mfma_f32_16x16x32_bf16 v[96:99], v[152:155], v[176:179], v[96:99]
	v_mfma_f32_16x16x32_bf16 v[84:87], v[144:147], v[184:187], v[84:87]
	v_mfma_f32_16x16x32_bf16 v[80:83], v[152:155], v[184:187], v[80:83]
	v_mfma_f32_16x16x32_bf16 v[132:135], v[148:151], v[164:167], v[132:135]
	v_mfma_f32_16x16x32_bf16 v[128:131], v[156:159], v[164:167], v[128:131]
	v_mfma_f32_16x16x32_bf16 v[116:119], v[148:151], v[172:175], v[116:119]
	v_mfma_f32_16x16x32_bf16 v[112:115], v[156:159], v[172:175], v[112:115]
	v_mfma_f32_16x16x32_bf16 v[100:103], v[148:151], v[180:183], v[100:103]
	v_mfma_f32_16x16x32_bf16 v[96:99], v[156:159], v[180:183], v[96:99]
	v_mfma_f32_16x16x32_bf16 v[84:87], v[148:151], v[188:191], v[84:87]
	v_mfma_f32_16x16x32_bf16 v[80:83], v[156:159], v[188:191], v[80:83]
	s_barrier
	s_add_i32 s78, s73, s54
	s_mov_b32 m0, s78
	ds_read_b128 v[160:163], v243 offset:16384
	ds_read_b128 v[164:167], v243 offset:17408
	ds_read_b128 v[168:171], v243 offset:18432
	ds_read_b128 v[172:175], v243 offset:19456
	ds_read_b128 v[176:179], v243 offset:20480
	ds_read_b128 v[180:183], v243 offset:21504
	ds_read_b128 v[184:187], v243 offset:22528
	ds_read_b128 v[188:191], v243 offset:23552
	global_load_lds_dwordx4 v210, s[50:51]
	s_add_i32 m0, s78, 0x2000
	s_add_u32 s78, s50, 0x200000
	s_addc_u32 s79, s51, 0
	s_add_i32 s80, s74, s54
	global_load_lds_dwordx4 v214, s[50:51]
	s_mov_b32 m0, s80
	s_nop 0
	global_load_lds_dwordx4 v210, s[78:79]
	s_add_i32 m0, s80, 0x2000
	s_nop 0
	global_load_lds_dwordx4 v214, s[78:79]
	s_mov_b32 m0, s55
	s_nop 0
	global_load_lds_dwordx4 v208, s[52:53]
	s_mov_b32 m0, s56
	s_nop 0
	global_load_lds_dwordx4 v212, s[52:53]
	s_waitcnt vmcnt(8)
	s_waitcnt lgkmcnt(0)
	s_barrier
	s_waitcnt lgkmcnt(0)
	v_mfma_f32_16x16x32_bf16 v[76:79], v[56:59], v[160:163], v[76:79]
	v_mfma_f32_16x16x32_bf16 v[72:75], v[64:67], v[160:163], v[72:75]
	v_mfma_f32_16x16x32_bf16 v[44:47], v[56:59], v[168:171], v[44:47]
	v_mfma_f32_16x16x32_bf16 v[40:43], v[64:67], v[168:171], v[40:43]
	v_mfma_f32_16x16x32_bf16 v[28:31], v[56:59], v[176:179], v[28:31]
	v_mfma_f32_16x16x32_bf16 v[24:27], v[64:67], v[176:179], v[24:27]
	v_mfma_f32_16x16x32_bf16 v[12:15], v[56:59], v[184:187], v[12:15]
	v_mfma_f32_16x16x32_bf16 v[8:11], v[64:67], v[184:187], v[8:11]
	v_mfma_f32_16x16x32_bf16 v[76:79], v[60:63], v[164:167], v[76:79]
	v_mfma_f32_16x16x32_bf16 v[72:75], v[68:71], v[164:167], v[72:75]
	v_mfma_f32_16x16x32_bf16 v[44:47], v[60:63], v[172:175], v[44:47]
	v_mfma_f32_16x16x32_bf16 v[40:43], v[68:71], v[172:175], v[40:43]
	v_mfma_f32_16x16x32_bf16 v[28:31], v[60:63], v[180:183], v[28:31]
	v_mfma_f32_16x16x32_bf16 v[24:27], v[68:71], v[180:183], v[24:27]
	v_mfma_f32_16x16x32_bf16 v[12:15], v[60:63], v[188:191], v[12:15]
	v_mfma_f32_16x16x32_bf16 v[8:11], v[68:71], v[188:191], v[8:11]
	v_mfma_f32_16x16x32_bf16 v[52:55], v[144:147], v[160:163], v[52:55]
	v_mfma_f32_16x16x32_bf16 v[48:51], v[152:155], v[160:163], v[48:51]
	v_mfma_f32_16x16x32_bf16 v[36:39], v[144:147], v[168:171], v[36:39]
	v_mfma_f32_16x16x32_bf16 v[32:35], v[152:155], v[168:171], v[32:35]
	v_mfma_f32_16x16x32_bf16 v[20:23], v[144:147], v[176:179], v[20:23]
	v_mfma_f32_16x16x32_bf16 v[16:19], v[152:155], v[176:179], v[16:19]
	v_mfma_f32_16x16x32_bf16 v[4:7], v[144:147], v[184:187], v[4:7]
	v_mfma_f32_16x16x32_bf16 v[0:3], v[152:155], v[184:187], v[0:3]
	v_mfma_f32_16x16x32_bf16 v[52:55], v[148:151], v[164:167], v[52:55]
	v_mfma_f32_16x16x32_bf16 v[48:51], v[156:159], v[164:167], v[48:51]
	v_mfma_f32_16x16x32_bf16 v[36:39], v[148:151], v[172:175], v[36:39]
	v_mfma_f32_16x16x32_bf16 v[32:35], v[156:159], v[172:175], v[32:35]
	v_mfma_f32_16x16x32_bf16 v[20:23], v[148:151], v[180:183], v[20:23]
	v_mfma_f32_16x16x32_bf16 v[16:19], v[156:159], v[180:183], v[16:19]
	v_mfma_f32_16x16x32_bf16 v[4:7], v[148:151], v[188:191], v[4:7]
	v_mfma_f32_16x16x32_bf16 v[0:3], v[156:159], v[188:191], v[0:3]
	s_barrier
	s_add_i32 s78, 0, 0x18000
	s_add_i32 s79, 0, 0x1c000
	v_add_u32_e32 v68, s78, v239
	v_add_u32_e32 v156, s79, v239
	ds_read_b128 v[56:59], v68
	ds_read_b128 v[60:63], v68 offset:1024
	ds_read_b128 v[64:67], v68 offset:2048
	ds_read_b128 v[68:71], v68 offset:3072
	ds_read_b128 v[144:147], v156
	ds_read_b128 v[148:151], v156 offset:1024
	ds_read_b128 v[152:155], v156 offset:2048
	ds_read_b128 v[156:159], v156 offset:3072
	s_add_u32 s52, s52, 0x200000
	s_addc_u32 s53, s53, 0
	s_mov_b32 m0, s57
	ds_read_b128 v[160:163], v243 offset:32768
	ds_read_b128 v[164:167], v243 offset:33792
	ds_read_b128 v[168:171], v243 offset:34816
	ds_read_b128 v[172:175], v243 offset:35840
	ds_read_b128 v[176:179], v243 offset:36864
	ds_read_b128 v[180:183], v243 offset:37888
	ds_read_b128 v[184:187], v243 offset:38912
	ds_read_b128 v[188:191], v243 offset:39936
	global_load_lds_dwordx4 v208, s[52:53]
	s_mov_b32 m0, s58
	s_nop 0
	global_load_lds_dwordx4 v212, s[52:53]
	s_waitcnt vmcnt(8)
	s_waitcnt lgkmcnt(0)
	s_barrier
	s_waitcnt lgkmcnt(0)
	v_mfma_f32_16x16x32_bf16 v[140:143], v[56:59], v[160:163], v[140:143]
	v_mfma_f32_16x16x32_bf16 v[136:139], v[64:67], v[160:163], v[136:139]
	v_mfma_f32_16x16x32_bf16 v[124:127], v[56:59], v[168:171], v[124:127]
	v_mfma_f32_16x16x32_bf16 v[120:123], v[64:67], v[168:171], v[120:123]
	v_mfma_f32_16x16x32_bf16 v[108:111], v[56:59], v[176:179], v[108:111]
	v_mfma_f32_16x16x32_bf16 v[104:107], v[64:67], v[176:179], v[104:107]
	v_mfma_f32_16x16x32_bf16 v[92:95], v[56:59], v[184:187], v[92:95]
	v_mfma_f32_16x16x32_bf16 v[88:91], v[64:67], v[184:187], v[88:91]
	v_mfma_f32_16x16x32_bf16 v[140:143], v[60:63], v[164:167], v[140:143]
	v_mfma_f32_16x16x32_bf16 v[136:139], v[68:71], v[164:167], v[136:139]
	v_mfma_f32_16x16x32_bf16 v[124:127], v[60:63], v[172:175], v[124:127]
	v_mfma_f32_16x16x32_bf16 v[120:123], v[68:71], v[172:175], v[120:123]
	v_mfma_f32_16x16x32_bf16 v[108:111], v[60:63], v[180:183], v[108:111]
	v_mfma_f32_16x16x32_bf16 v[104:107], v[68:71], v[180:183], v[104:107]
	v_mfma_f32_16x16x32_bf16 v[92:95], v[60:63], v[188:191], v[92:95]
	v_mfma_f32_16x16x32_bf16 v[88:91], v[68:71], v[188:191], v[88:91]
	v_mfma_f32_16x16x32_bf16 v[132:135], v[144:147], v[160:163], v[132:135]
	v_mfma_f32_16x16x32_bf16 v[128:131], v[152:155], v[160:163], v[128:131]
	v_mfma_f32_16x16x32_bf16 v[116:119], v[144:147], v[168:171], v[116:119]
	v_mfma_f32_16x16x32_bf16 v[112:115], v[152:155], v[168:171], v[112:115]
	v_mfma_f32_16x16x32_bf16 v[100:103], v[144:147], v[176:179], v[100:103]
	v_mfma_f32_16x16x32_bf16 v[96:99], v[152:155], v[176:179], v[96:99]
	v_mfma_f32_16x16x32_bf16 v[84:87], v[144:147], v[184:187], v[84:87]
	v_mfma_f32_16x16x32_bf16 v[80:83], v[152:155], v[184:187], v[80:83]
	v_mfma_f32_16x16x32_bf16 v[132:135], v[148:151], v[164:167], v[132:135]
	v_mfma_f32_16x16x32_bf16 v[128:131], v[156:159], v[164:167], v[128:131]
	v_mfma_f32_16x16x32_bf16 v[116:119], v[148:151], v[172:175], v[116:119]
	v_mfma_f32_16x16x32_bf16 v[112:115], v[156:159], v[172:175], v[112:115]
	v_mfma_f32_16x16x32_bf16 v[100:103], v[148:151], v[180:183], v[100:103]
	v_mfma_f32_16x16x32_bf16 v[96:99], v[156:159], v[180:183], v[96:99]
	v_mfma_f32_16x16x32_bf16 v[84:87], v[148:151], v[188:191], v[84:87]
	v_mfma_f32_16x16x32_bf16 v[80:83], v[156:159], v[188:191], v[80:83]
	s_barrier
	s_add_i32 s52, s78, s54
	s_mov_b32 m0, s52
	ds_read_b128 v[160:163], v243 offset:49152
	ds_read_b128 v[164:167], v243 offset:50176
	ds_read_b128 v[168:171], v243 offset:51200
	ds_read_b128 v[172:175], v243 offset:52224
	ds_read_b128 v[176:179], v243 offset:53248
	ds_read_b128 v[180:183], v243 offset:54272
	ds_read_b128 v[184:187], v243 offset:55296
	ds_read_b128 v[188:191], v243 offset:56320
	global_load_lds_dwordx4 v210, s[98:99]
	s_add_i32 m0, s52, 0x2000
	s_add_u32 s50, s50, 0x200080
	s_addc_u32 s51, s51, 0
	s_add_i32 s52, s79, s54
	global_load_lds_dwordx4 v214, s[98:99]
	s_mov_b32 m0, s52
	s_nop 0
	global_load_lds_dwordx4 v210, s[50:51]
	s_add_i32 m0, s52, 0x2000
	s_nop 0
	global_load_lds_dwordx4 v214, s[50:51]
	s_mov_b32 m0, s63
	s_nop 0
	global_load_lds_dwordx4 v208, s[100:101]
	s_mov_b32 m0, s68
	s_nop 0
	global_load_lds_dwordx4 v212, s[100:101]
	s_waitcnt vmcnt(8)
	s_waitcnt lgkmcnt(0)
	s_barrier
	s_waitcnt lgkmcnt(0)
	v_mfma_f32_16x16x32_bf16 v[76:79], v[56:59], v[160:163], v[76:79]
	v_mfma_f32_16x16x32_bf16 v[72:75], v[64:67], v[160:163], v[72:75]
	v_mfma_f32_16x16x32_bf16 v[44:47], v[56:59], v[168:171], v[44:47]
	v_mfma_f32_16x16x32_bf16 v[40:43], v[64:67], v[168:171], v[40:43]
	v_mfma_f32_16x16x32_bf16 v[28:31], v[56:59], v[176:179], v[28:31]
	v_mfma_f32_16x16x32_bf16 v[24:27], v[64:67], v[176:179], v[24:27]
	v_mfma_f32_16x16x32_bf16 v[12:15], v[56:59], v[184:187], v[12:15]
	v_mfma_f32_16x16x32_bf16 v[8:11], v[64:67], v[184:187], v[8:11]
	v_mfma_f32_16x16x32_bf16 v[76:79], v[60:63], v[164:167], v[76:79]
	v_mfma_f32_16x16x32_bf16 v[72:75], v[68:71], v[164:167], v[72:75]
	v_mfma_f32_16x16x32_bf16 v[44:47], v[60:63], v[172:175], v[44:47]
	v_mfma_f32_16x16x32_bf16 v[40:43], v[68:71], v[172:175], v[40:43]
	v_mfma_f32_16x16x32_bf16 v[28:31], v[60:63], v[180:183], v[28:31]
	v_mfma_f32_16x16x32_bf16 v[24:27], v[68:71], v[180:183], v[24:27]
	v_mfma_f32_16x16x32_bf16 v[12:15], v[60:63], v[188:191], v[12:15]
	v_mfma_f32_16x16x32_bf16 v[8:11], v[68:71], v[188:191], v[8:11]
	v_mfma_f32_16x16x32_bf16 v[52:55], v[144:147], v[160:163], v[52:55]
	v_mfma_f32_16x16x32_bf16 v[48:51], v[152:155], v[160:163], v[48:51]
	v_mfma_f32_16x16x32_bf16 v[36:39], v[144:147], v[168:171], v[36:39]
	v_mfma_f32_16x16x32_bf16 v[32:35], v[152:155], v[168:171], v[32:35]
	v_mfma_f32_16x16x32_bf16 v[20:23], v[144:147], v[176:179], v[20:23]
	v_mfma_f32_16x16x32_bf16 v[16:19], v[152:155], v[176:179], v[16:19]
	v_mfma_f32_16x16x32_bf16 v[4:7], v[144:147], v[184:187], v[4:7]
	v_mfma_f32_16x16x32_bf16 v[0:3], v[152:155], v[184:187], v[0:3]
	v_mfma_f32_16x16x32_bf16 v[52:55], v[148:151], v[164:167], v[52:55]
	v_mfma_f32_16x16x32_bf16 v[48:51], v[156:159], v[164:167], v[48:51]
	v_mfma_f32_16x16x32_bf16 v[36:39], v[148:151], v[172:175], v[36:39]
	v_mfma_f32_16x16x32_bf16 v[32:35], v[156:159], v[172:175], v[32:35]
	v_mfma_f32_16x16x32_bf16 v[20:23], v[148:151], v[180:183], v[20:23]
	v_mfma_f32_16x16x32_bf16 v[16:19], v[156:159], v[180:183], v[16:19]
	v_mfma_f32_16x16x32_bf16 v[4:7], v[148:151], v[188:191], v[4:7]
	v_mfma_f32_16x16x32_bf16 v[0:3], v[156:159], v[188:191], v[0:3]
	s_barrier
	s_add_i32 s77, s77, 2
	s_add_u32 s46, s46, 0x100
	s_addc_u32 s47, s47, 0
	s_add_u32 s75, s75, 0x100
	s_addc_u32 s76, s76, 0
	s_cmpk_gt_u32 s77, 0x7d
	s_cbranch_scc0 .LBB0_815
	s_and_b64 vcc, exec, s[14:15]
	s_cbranch_vccz .LBB0_818
	s_barrier
